# top-k butterflies via DPP row rotations; A0 gather 8 loads in flight; weight-conversion tile loop rewritten as 4-deep pipelined ring with scalar tile descriptors; peW1 dot loop 16 loads in flight
# speedup vs baseline: 1.1022x; 1.0446x over previous
; __device__ __forceinline__ float wave_max(float v) {
; #pragma unroll
;     for (int o = 8; o >= 1; o >>= 1) v = fmaxf(v, __shfl_xor(v, o));
;     return rows_max(v); }
; __device__ __forceinline__ void nsa_unit(LAS unsigned char* lds, const Ctx& P, int l, int b, int hkv, int tb) {
;     ...
;         for (int tt = 0; tt < 8; ++tt) { const int tl = 8 * wid + tt;
;             unsigned long long mask;
;             if (qb <= 7) mask = (2ull << qb) - 1ull;
;             else {
;                 const float v = impb[(0 * 64 + tl) * 64 + lane] + impb[(1 * 64 + tl) * 64 + lane] + impb[(2 * 64 + tl) * 64 + lane] + impb[(3 * 64 + tl) * 64 + lane];
;                 float vv = (lane >= 1 && lane <= qb - 2) ? v : -__builtin_inff();
;                 mask = 1ull | (1ull << qb) | (1ull << (qb - 1));
; #pragma unroll
;                 for (int r = 0; r < 5; ++r) { const float mx = wave_max(vv); const unsigned long long bal = __ballot(vv == mx);
;                     const int js = __builtin_ctzll(bal); mask |= 1ull << js; if (lane == js) vv = -__builtin_inff(); }
;             }
;             if (lane == 0) sels[tl] = mask; }
.LBB0_364:
	s_or_b64 exec, exec, s[18:19]
	v_and_b32_e32 v19, 64, v239
	v_add_u32_e32 v19, 64, v19
	v_xor_b32_e32 v20, 8, v239
	v_cmp_lt_i32_e32 vcc, v20, v19
	v_xor_b32_e32 v22, 4, v239
	v_max_f32_e32 v23, v18, v18
	v_cndmask_b32_e32 v20, v239, v20, vcc
	v_lshlrev_b32_e32 v20, 2, v20
	s_nop 1
	v_mov_b32_dpp v21, v18 row_ror:8 row_mask:0xf bank_mask:0xf
	v_cmp_lt_i32_e32 vcc, v22, v19
	v_xor_b32_e32 v24, 2, v239
	v_xor_b32_e32 v25, 1, v239
	v_cndmask_b32_e32 v22, v239, v22, vcc
	s_waitcnt lgkmcnt(0)
	v_max_f32_e32 v21, v21, v21
	v_lshlrev_b32_e32 v22, 2, v22
	v_max_f32_e32 v21, v23, v21
	s_nop 1
	v_mov_b32_dpp v23, v21 row_ror:4 row_mask:0xf bank_mask:0xf
	v_cmp_lt_i32_e32 vcc, v24, v19
	s_waitcnt lgkmcnt(0)
	v_max_f32_e32 v23, v23, v23
	v_cndmask_b32_e32 v24, v239, v24, vcc
	v_lshlrev_b32_e32 v24, 2, v24
	v_max_f32_e32 v21, v21, v23
	s_nop 1
	v_mov_b32_dpp v23, v21 row_ror:2 row_mask:0xf bank_mask:0xf
	v_cmp_lt_i32_e32 vcc, v25, v19
	s_waitcnt lgkmcnt(0)
	v_max_f32_e32 v23, v23, v23
	v_cndmask_b32_e32 v19, v239, v25, vcc
	v_lshlrev_b32_e32 v19, 2, v19
	v_max_f32_e32 v21, v21, v23
	s_nop 1
	v_mov_b32_dpp v23, v21 row_ror:1 row_mask:0xf bank_mask:0xf
	s_waitcnt lgkmcnt(0)
	v_max_f32_e32 v23, v23, v23
	v_max_f32_e32 v21, v21, v23
	v_mov_b32_e32 v23, v21
	s_nop 1
	v_permlane16_swap_b32_e32 v21, v23
	v_max_f32_e32 v23, v23, v23
	v_max_f32_e32 v21, v21, v21
	v_max_f32_e32 v21, v21, v23
	v_mov_b32_e32 v23, v21
	s_nop 1
	v_permlane32_swap_b32_e32 v21, v23
	v_max_f32_e32 v23, v23, v23
	v_max_f32_e32 v21, v21, v21
	v_max_f32_e32 v21, v21, v23
	v_cmp_eq_f32_e32 vcc, v18, v21
	s_ff1_i32_b64 s18, vcc
	v_cmp_ne_u32_e32 vcc, s18, v99
	s_lshl_b64 s[18:19], 1, s18
	s_nop 0
	v_cndmask_b32_e32 v18, v242, v18, vcc
	s_nop 1
	v_mov_b32_dpp v21, v18 row_ror:8 row_mask:0xf bank_mask:0xf
	v_max_f32_e32 v23, v18, v18
	s_waitcnt lgkmcnt(0)
	v_max_f32_e32 v21, v21, v21
	v_max_f32_e32 v21, v23, v21
	s_nop 1
	v_mov_b32_dpp v23, v21 row_ror:4 row_mask:0xf bank_mask:0xf
	s_waitcnt lgkmcnt(0)
	v_max_f32_e32 v23, v23, v23
	v_max_f32_e32 v21, v21, v23
	s_nop 1
	v_mov_b32_dpp v23, v21 row_ror:2 row_mask:0xf bank_mask:0xf
	s_waitcnt lgkmcnt(0)
	v_max_f32_e32 v23, v23, v23
	v_max_f32_e32 v21, v21, v23
	s_nop 1
	v_mov_b32_dpp v23, v21 row_ror:1 row_mask:0xf bank_mask:0xf
	s_waitcnt lgkmcnt(0)
	v_max_f32_e32 v23, v23, v23
	v_max_f32_e32 v21, v21, v23
	v_mov_b32_e32 v23, v21
	s_nop 1
	v_permlane16_swap_b32_e32 v21, v23
	v_max_f32_e32 v23, v23, v23
	v_max_f32_e32 v21, v21, v21
	v_max_f32_e32 v21, v21, v23
	v_mov_b32_e32 v23, v21
	s_nop 1
	v_permlane32_swap_b32_e32 v21, v23
	v_max_f32_e32 v23, v23, v23
	v_max_f32_e32 v21, v21, v21
	v_max_f32_e32 v21, v21, v23
	v_cmp_eq_f32_e32 vcc, v18, v21
	s_ff1_i32_b64 s20, vcc
	v_cmp_ne_u32_e32 vcc, s20, v99
	s_lshl_b64 s[20:21], 1, s20
	s_nop 0
	v_cndmask_b32_e32 v18, v242, v18, vcc
	s_nop 1
	v_mov_b32_dpp v21, v18 row_ror:8 row_mask:0xf bank_mask:0xf
	v_max_f32_e32 v23, v18, v18
	s_waitcnt lgkmcnt(0)
	v_max_f32_e32 v21, v21, v21
	v_max_f32_e32 v21, v23, v21
	s_nop 1
	v_mov_b32_dpp v23, v21 row_ror:4 row_mask:0xf bank_mask:0xf
	s_waitcnt lgkmcnt(0)
	v_max_f32_e32 v23, v23, v23
	v_max_f32_e32 v21, v21, v23
	s_nop 1
	v_mov_b32_dpp v23, v21 row_ror:2 row_mask:0xf bank_mask:0xf
	s_waitcnt lgkmcnt(0)
	v_max_f32_e32 v23, v23, v23
	v_max_f32_e32 v21, v21, v23
	s_nop 1
	v_mov_b32_dpp v23, v21 row_ror:1 row_mask:0xf bank_mask:0xf
	s_waitcnt lgkmcnt(0)
	v_max_f32_e32 v23, v23, v23
	v_max_f32_e32 v21, v21, v23
	v_mov_b32_e32 v23, v21
	s_nop 1
	v_permlane16_swap_b32_e32 v21, v23
	v_max_f32_e32 v23, v23, v23
	v_max_f32_e32 v21, v21, v21
	v_max_f32_e32 v21, v21, v23
	v_mov_b32_e32 v23, v21
	s_nop 1
	v_permlane32_swap_b32_e32 v21, v23
	v_max_f32_e32 v23, v23, v23
	v_max_f32_e32 v21, v21, v21
	v_max_f32_e32 v21, v21, v23
	v_cmp_eq_f32_e32 vcc, v18, v21
	s_ff1_i32_b64 s26, vcc
	v_cmp_ne_u32_e32 vcc, s26, v99
	s_lshl_b64 s[26:27], 1, s26
	s_nop 0
	v_cndmask_b32_e32 v18, v242, v18, vcc
	s_nop 1
	v_mov_b32_dpp v21, v18 row_ror:8 row_mask:0xf bank_mask:0xf
	v_max_f32_e32 v23, v18, v18
	s_waitcnt lgkmcnt(0)
	v_max_f32_e32 v21, v21, v21
	v_max_f32_e32 v21, v23, v21
	s_nop 1
	v_mov_b32_dpp v23, v21 row_ror:4 row_mask:0xf bank_mask:0xf
	s_waitcnt lgkmcnt(0)
	v_max_f32_e32 v23, v23, v23
	v_max_f32_e32 v21, v21, v23
	s_nop 1
	v_mov_b32_dpp v23, v21 row_ror:2 row_mask:0xf bank_mask:0xf
	s_waitcnt lgkmcnt(0)
	v_max_f32_e32 v23, v23, v23
	v_max_f32_e32 v21, v21, v23
	s_nop 1
	v_mov_b32_dpp v23, v21 row_ror:1 row_mask:0xf bank_mask:0xf
	s_waitcnt lgkmcnt(0)
	v_max_f32_e32 v23, v23, v23
	v_max_f32_e32 v21, v21, v23
	v_mov_b32_e32 v23, v21
	s_nop 1
	v_permlane16_swap_b32_e32 v21, v23
	v_max_f32_e32 v23, v23, v23
	v_max_f32_e32 v21, v21, v21
	v_max_f32_e32 v21, v21, v23
	v_mov_b32_e32 v23, v21
	s_nop 1
	v_permlane32_swap_b32_e32 v21, v23
	v_max_f32_e32 v23, v23, v23
	v_max_f32_e32 v21, v21, v21
	v_max_f32_e32 v21, v21, v23
	v_cmp_eq_f32_e32 vcc, v18, v21
	s_ff1_i32_b64 s28, vcc
	v_cmp_ne_u32_e32 vcc, s28, v99
	s_lshl_b64 s[28:29], 1, s28
	s_nop 0
	v_cndmask_b32_e32 v18, v242, v18, vcc
	s_nop 1
	v_mov_b32_dpp v20, v18 row_ror:8 row_mask:0xf bank_mask:0xf
	v_max_f32_e32 v21, v18, v18
	s_waitcnt lgkmcnt(0)
	v_max_f32_e32 v20, v20, v20
	v_max_f32_e32 v20, v21, v20
	s_nop 1
	v_mov_b32_dpp v21, v20 row_ror:4 row_mask:0xf bank_mask:0xf
	s_waitcnt lgkmcnt(0)
	v_max_f32_e32 v21, v21, v21
	v_max_f32_e32 v20, v20, v21
	s_nop 1
	v_mov_b32_dpp v21, v20 row_ror:2 row_mask:0xf bank_mask:0xf
	s_waitcnt lgkmcnt(0)
	v_max_f32_e32 v21, v21, v21
	v_max_f32_e32 v20, v20, v21
	s_nop 1
	v_mov_b32_dpp v19, v20 row_ror:1 row_mask:0xf bank_mask:0xf
	s_waitcnt lgkmcnt(0)
	v_max_f32_e32 v19, v19, v19
	v_max_f32_e32 v19, v20, v19
	v_mov_b32_e32 v20, v19
	s_nop 1
	v_permlane16_swap_b32_e32 v19, v20
	v_max_f32_e32 v20, v20, v20
	v_max_f32_e32 v19, v19, v19
	v_max_f32_e32 v19, v19, v20
	v_mov_b32_e32 v20, v19
	s_nop 1
	v_permlane32_swap_b32_e32 v19, v20
	v_max_f32_e32 v20, v20, v20
	v_max_f32_e32 v19, v19, v19
	v_max_f32_e32 v19, v19, v20
	v_cmp_eq_f32_e32 vcc, v18, v19
	s_sub_u32 s30, 0, vcc_lo
	s_subb_u32 s31, 0, vcc_hi
	s_or_b64 s[18:19], s[18:19], s[20:21]
	s_or_b64 s[18:19], s[18:19], s[26:27]
	s_and_b64 s[20:21], vcc, s[30:31]
	s_or_b64 s[18:19], s[18:19], s[28:29]
	s_or_b64 s[18:19], s[18:19], s[20:21]
	s_or_b64 s[18:19], s[18:19], s[0:1]

; __device__ __forceinline__ float wave_max(float v) {
; #pragma unroll
;     for (int o = 8; o >= 1; o >>= 1) v = fmaxf(v, __shfl_xor(v, o));
;     return rows_max(v); }
; __device__ __forceinline__ void nsa_unit(LAS unsigned char* lds, const Ctx& P, int l, int b, int hkv, int tb) {
;     ...
;         for (int tt = 0; tt < 8; ++tt) { const int tl = 8 * wid + tt;
;             unsigned long long mask;
;             if (qb <= 7) mask = (2ull << qb) - 1ull;
;             else {
;                 const float v = impb[(0 * 64 + tl) * 64 + lane] + impb[(1 * 64 + tl) * 64 + lane] + impb[(2 * 64 + tl) * 64 + lane] + impb[(3 * 64 + tl) * 64 + lane];
;                 float vv = (lane >= 1 && lane <= qb - 2) ? v : -__builtin_inff();
;                 mask = 1ull | (1ull << qb) | (1ull << (qb - 1));
; #pragma unroll
;                 for (int r = 0; r < 5; ++r) { const float mx = wave_max(vv); const unsigned long long bal = __ballot(vv == mx);
;                     const int js = __builtin_ctzll(bal); mask |= 1ull << js; if (lane == js) vv = -__builtin_inff(); }
;             }
;             if (lane == 0) sels[tl] = mask; }
.LBB0_370:
	s_or_b64 exec, exec, s[8:9]
	v_and_b32_e32 v21, 64, v239
	v_add_u32_e32 v21, 64, v21
	v_xor_b32_e32 v22, 8, v239
	v_cmp_lt_i32_e32 vcc, v22, v21
	v_xor_b32_e32 v24, 4, v239
	v_max_f32_e32 v25, v20, v20
	v_cndmask_b32_e32 v22, v239, v22, vcc
	v_lshlrev_b32_e32 v22, 2, v22
	s_nop 1
	v_mov_b32_dpp v23, v20 row_ror:8 row_mask:0xf bank_mask:0xf
	v_cmp_lt_i32_e32 vcc, v24, v21
	v_xor_b32_e32 v26, 2, v239
	v_xor_b32_e32 v27, 1, v239
	v_cndmask_b32_e32 v24, v239, v24, vcc
	s_waitcnt lgkmcnt(0)
	v_max_f32_e32 v23, v23, v23
	v_lshlrev_b32_e32 v24, 2, v24
	v_max_f32_e32 v23, v25, v23
	s_nop 1
	v_mov_b32_dpp v25, v23 row_ror:4 row_mask:0xf bank_mask:0xf
	v_cmp_lt_i32_e32 vcc, v26, v21
	s_waitcnt lgkmcnt(0)
	v_max_f32_e32 v25, v25, v25
	v_cndmask_b32_e32 v26, v239, v26, vcc
	v_lshlrev_b32_e32 v26, 2, v26
	v_max_f32_e32 v23, v23, v25
	s_nop 1
	v_mov_b32_dpp v25, v23 row_ror:2 row_mask:0xf bank_mask:0xf
	v_cmp_lt_i32_e32 vcc, v27, v21
	s_waitcnt lgkmcnt(0)
	v_max_f32_e32 v25, v25, v25
	v_cndmask_b32_e32 v21, v239, v27, vcc
	v_lshlrev_b32_e32 v21, 2, v21
	v_max_f32_e32 v23, v23, v25
	s_nop 1
	v_mov_b32_dpp v25, v23 row_ror:1 row_mask:0xf bank_mask:0xf
	s_waitcnt lgkmcnt(0)
	v_max_f32_e32 v25, v25, v25
	v_max_f32_e32 v23, v23, v25
	v_mov_b32_e32 v25, v23
	s_nop 1
	v_permlane16_swap_b32_e32 v23, v25
	v_max_f32_e32 v25, v25, v25
	v_max_f32_e32 v23, v23, v23
	v_max_f32_e32 v23, v23, v25
	v_mov_b32_e32 v25, v23
	s_nop 1
	v_permlane32_swap_b32_e32 v23, v25
	v_max_f32_e32 v25, v25, v25
	v_max_f32_e32 v23, v23, v23
	v_max_f32_e32 v23, v23, v25
	v_cmp_eq_f32_e32 vcc, v20, v23
	s_ff1_i32_b64 s8, vcc
	v_cmp_ne_u32_e32 vcc, s8, v99
	s_lshl_b64 s[8:9], 1, s8
	s_nop 0
	v_cndmask_b32_e32 v20, v242, v20, vcc
	s_nop 1
	v_mov_b32_dpp v23, v20 row_ror:8 row_mask:0xf bank_mask:0xf
	v_max_f32_e32 v25, v20, v20
	s_waitcnt lgkmcnt(0)
	v_max_f32_e32 v23, v23, v23
	v_max_f32_e32 v23, v25, v23
	s_nop 1
	v_mov_b32_dpp v25, v23 row_ror:4 row_mask:0xf bank_mask:0xf
	s_waitcnt lgkmcnt(0)
	v_max_f32_e32 v25, v25, v25
	v_max_f32_e32 v23, v23, v25
	s_nop 1
	v_mov_b32_dpp v25, v23 row_ror:2 row_mask:0xf bank_mask:0xf
	s_waitcnt lgkmcnt(0)
	v_max_f32_e32 v25, v25, v25
	v_max_f32_e32 v23, v23, v25
	s_nop 1
	v_mov_b32_dpp v25, v23 row_ror:1 row_mask:0xf bank_mask:0xf
	s_waitcnt lgkmcnt(0)
	v_max_f32_e32 v25, v25, v25
	v_max_f32_e32 v23, v23, v25
	v_mov_b32_e32 v25, v23
	s_nop 1
	v_permlane16_swap_b32_e32 v23, v25
	v_max_f32_e32 v25, v25, v25
	v_max_f32_e32 v23, v23, v23
	v_max_f32_e32 v23, v23, v25
	v_mov_b32_e32 v25, v23
	s_nop 1
	v_permlane32_swap_b32_e32 v23, v25
	v_max_f32_e32 v25, v25, v25
	v_max_f32_e32 v23, v23, v23
	v_max_f32_e32 v23, v23, v25
	v_cmp_eq_f32_e32 vcc, v20, v23
	s_ff1_i32_b64 s20, vcc
	v_cmp_ne_u32_e32 vcc, s20, v99
	s_lshl_b64 s[20:21], 1, s20
	s_nop 0
	v_cndmask_b32_e32 v20, v242, v20, vcc
	s_nop 1
	v_mov_b32_dpp v23, v20 row_ror:8 row_mask:0xf bank_mask:0xf
	v_max_f32_e32 v25, v20, v20
	s_waitcnt lgkmcnt(0)
	v_max_f32_e32 v23, v23, v23
	v_max_f32_e32 v23, v25, v23
	s_nop 1
	v_mov_b32_dpp v25, v23 row_ror:4 row_mask:0xf bank_mask:0xf
	s_waitcnt lgkmcnt(0)
	v_max_f32_e32 v25, v25, v25
	v_max_f32_e32 v23, v23, v25
	s_nop 1
	v_mov_b32_dpp v25, v23 row_ror:2 row_mask:0xf bank_mask:0xf
	s_waitcnt lgkmcnt(0)
	v_max_f32_e32 v25, v25, v25
	v_max_f32_e32 v23, v23, v25
	s_nop 1
	v_mov_b32_dpp v25, v23 row_ror:1 row_mask:0xf bank_mask:0xf
	s_waitcnt lgkmcnt(0)
	v_max_f32_e32 v25, v25, v25
	v_max_f32_e32 v23, v23, v25
	v_mov_b32_e32 v25, v23
	s_nop 1
	v_permlane16_swap_b32_e32 v23, v25
	v_max_f32_e32 v25, v25, v25
	v_max_f32_e32 v23, v23, v23
	v_max_f32_e32 v23, v23, v25
	v_mov_b32_e32 v25, v23
	s_nop 1
	v_permlane32_swap_b32_e32 v23, v25
	v_max_f32_e32 v25, v25, v25
	v_max_f32_e32 v23, v23, v23
	v_max_f32_e32 v23, v23, v25
	v_cmp_eq_f32_e32 vcc, v20, v23
	s_ff1_i32_b64 s26, vcc
	v_cmp_ne_u32_e32 vcc, s26, v99
	s_lshl_b64 s[26:27], 1, s26
	s_nop 0
	v_cndmask_b32_e32 v20, v242, v20, vcc
	s_nop 1
	v_mov_b32_dpp v23, v20 row_ror:8 row_mask:0xf bank_mask:0xf
	v_max_f32_e32 v25, v20, v20
	s_waitcnt lgkmcnt(0)
	v_max_f32_e32 v23, v23, v23
	v_max_f32_e32 v23, v25, v23
	s_nop 1
	v_mov_b32_dpp v25, v23 row_ror:4 row_mask:0xf bank_mask:0xf
	s_waitcnt lgkmcnt(0)
	v_max_f32_e32 v25, v25, v25
	v_max_f32_e32 v23, v23, v25
	s_nop 1
	v_mov_b32_dpp v25, v23 row_ror:2 row_mask:0xf bank_mask:0xf
	s_waitcnt lgkmcnt(0)
	v_max_f32_e32 v25, v25, v25
	v_max_f32_e32 v23, v23, v25
	s_nop 1
	v_mov_b32_dpp v25, v23 row_ror:1 row_mask:0xf bank_mask:0xf
	s_waitcnt lgkmcnt(0)
	v_max_f32_e32 v25, v25, v25
	v_max_f32_e32 v23, v23, v25
	v_mov_b32_e32 v25, v23
	s_nop 1
	v_permlane16_swap_b32_e32 v23, v25
	v_max_f32_e32 v25, v25, v25
	v_max_f32_e32 v23, v23, v23
	v_max_f32_e32 v23, v23, v25
	v_mov_b32_e32 v25, v23
	s_nop 1
	v_permlane32_swap_b32_e32 v23, v25
	v_max_f32_e32 v25, v25, v25
	v_max_f32_e32 v23, v23, v23
	v_max_f32_e32 v23, v23, v25
	v_cmp_eq_f32_e32 vcc, v20, v23
	s_ff1_i32_b64 s28, vcc
	v_cmp_ne_u32_e32 vcc, s28, v99
	s_lshl_b64 s[28:29], 1, s28
	s_nop 0
	v_cndmask_b32_e32 v20, v242, v20, vcc
	s_nop 1
	v_mov_b32_dpp v22, v20 row_ror:8 row_mask:0xf bank_mask:0xf
	v_max_f32_e32 v23, v20, v20
	s_waitcnt lgkmcnt(0)
	v_max_f32_e32 v22, v22, v22
	v_max_f32_e32 v22, v23, v22
	s_nop 1
	v_mov_b32_dpp v23, v22 row_ror:4 row_mask:0xf bank_mask:0xf
	s_waitcnt lgkmcnt(0)
	v_max_f32_e32 v23, v23, v23
	v_max_f32_e32 v22, v22, v23
	s_nop 1
	v_mov_b32_dpp v23, v22 row_ror:2 row_mask:0xf bank_mask:0xf
	s_waitcnt lgkmcnt(0)
	v_max_f32_e32 v23, v23, v23
	v_max_f32_e32 v22, v22, v23
	s_nop 1
	v_mov_b32_dpp v21, v22 row_ror:1 row_mask:0xf bank_mask:0xf
	s_waitcnt lgkmcnt(0)
	v_max_f32_e32 v21, v21, v21
	v_max_f32_e32 v21, v22, v21
	v_mov_b32_e32 v22, v21
	s_nop 1
	v_permlane16_swap_b32_e32 v21, v22
	v_max_f32_e32 v22, v22, v22
	v_max_f32_e32 v21, v21, v21
	v_max_f32_e32 v21, v21, v22
	v_mov_b32_e32 v22, v21
	s_nop 1
	v_permlane32_swap_b32_e32 v21, v22
	v_max_f32_e32 v22, v22, v22
	v_max_f32_e32 v21, v21, v21
	v_max_f32_e32 v21, v21, v22
	v_cmp_eq_f32_e32 vcc, v20, v21
	s_sub_u32 s30, 0, vcc_lo
	s_subb_u32 s31, 0, vcc_hi
	s_or_b64 s[8:9], s[8:9], s[20:21]
	s_or_b64 s[8:9], s[8:9], s[26:27]
	s_and_b64 s[20:21], vcc, s[30:31]
	s_or_b64 s[8:9], s[8:9], s[28:29]
	s_or_b64 s[8:9], s[8:9], s[20:21]
	s_or_b64 s[8:9], s[8:9], s[0:1]

; __device__ __forceinline__ float wave_max(float v) {
; #pragma unroll
;     for (int o = 8; o >= 1; o >>= 1) v = fmaxf(v, __shfl_xor(v, o));
;     return rows_max(v); }
; __device__ __forceinline__ void nsa_unit(LAS unsigned char* lds, const Ctx& P, int l, int b, int hkv, int tb) {
;     ...
;         for (int tt = 0; tt < 8; ++tt) { const int tl = 8 * wid + tt;
;             unsigned long long mask;
;             if (qb <= 7) mask = (2ull << qb) - 1ull;
;             else {
;                 const float v = impb[(0 * 64 + tl) * 64 + lane] + impb[(1 * 64 + tl) * 64 + lane] + impb[(2 * 64 + tl) * 64 + lane] + impb[(3 * 64 + tl) * 64 + lane];
;                 float vv = (lane >= 1 && lane <= qb - 2) ? v : -__builtin_inff();
;                 mask = 1ull | (1ull << qb) | (1ull << (qb - 1));
; #pragma unroll
;                 for (int r = 0; r < 5; ++r) { const float mx = wave_max(vv); const unsigned long long bal = __ballot(vv == mx);
;                     const int js = __builtin_ctzll(bal); mask |= 1ull << js; if (lane == js) vv = -__builtin_inff(); }
;             }
;             if (lane == 0) sels[tl] = mask; }
.LBB0_591:
	s_or_b64 exec, exec, s[8:9]
	v_and_b32_e32 v21, 64, v239
	v_add_u32_e32 v21, 64, v21
	v_xor_b32_e32 v22, 8, v239
	v_cmp_lt_i32_e32 vcc, v22, v21
	v_xor_b32_e32 v24, 4, v239
	v_max_f32_e32 v25, v20, v20
	v_cndmask_b32_e32 v22, v239, v22, vcc
	v_lshlrev_b32_e32 v22, 2, v22
	s_nop 1
	v_mov_b32_dpp v23, v20 row_ror:8 row_mask:0xf bank_mask:0xf
	v_cmp_lt_i32_e32 vcc, v24, v21
	v_xor_b32_e32 v26, 2, v239
	v_xor_b32_e32 v27, 1, v239
	v_cndmask_b32_e32 v24, v239, v24, vcc
	s_waitcnt lgkmcnt(0)
	v_max_f32_e32 v23, v23, v23
	v_lshlrev_b32_e32 v24, 2, v24
	v_max_f32_e32 v23, v25, v23
	s_nop 1
	v_mov_b32_dpp v25, v23 row_ror:4 row_mask:0xf bank_mask:0xf
	v_cmp_lt_i32_e32 vcc, v26, v21
	s_waitcnt lgkmcnt(0)
	v_max_f32_e32 v25, v25, v25
	v_cndmask_b32_e32 v26, v239, v26, vcc
	v_lshlrev_b32_e32 v26, 2, v26
	v_max_f32_e32 v23, v23, v25
	s_nop 1
	v_mov_b32_dpp v25, v23 row_ror:2 row_mask:0xf bank_mask:0xf
	v_cmp_lt_i32_e32 vcc, v27, v21
	s_waitcnt lgkmcnt(0)
	v_max_f32_e32 v25, v25, v25
	v_cndmask_b32_e32 v21, v239, v27, vcc
	v_lshlrev_b32_e32 v21, 2, v21
	v_max_f32_e32 v23, v23, v25
	s_nop 1
	v_mov_b32_dpp v25, v23 row_ror:1 row_mask:0xf bank_mask:0xf
	s_waitcnt lgkmcnt(0)
	v_max_f32_e32 v25, v25, v25
	v_max_f32_e32 v23, v23, v25
	v_mov_b32_e32 v25, v23
	s_nop 1
	v_permlane16_swap_b32_e32 v23, v25
	v_max_f32_e32 v25, v25, v25
	v_max_f32_e32 v23, v23, v23
	v_max_f32_e32 v23, v23, v25
	v_mov_b32_e32 v25, v23
	s_nop 1
	v_permlane32_swap_b32_e32 v23, v25
	v_max_f32_e32 v25, v25, v25
	v_max_f32_e32 v23, v23, v23
	v_max_f32_e32 v23, v23, v25
	v_cmp_eq_f32_e32 vcc, v20, v23
	s_ff1_i32_b64 s8, vcc
	v_cmp_ne_u32_e32 vcc, s8, v99
	s_lshl_b64 s[8:9], 1, s8
	s_nop 0
	v_cndmask_b32_e32 v20, v242, v20, vcc
	s_nop 1
	v_mov_b32_dpp v23, v20 row_ror:8 row_mask:0xf bank_mask:0xf
	v_max_f32_e32 v25, v20, v20
	s_waitcnt lgkmcnt(0)
	v_max_f32_e32 v23, v23, v23
	v_max_f32_e32 v23, v25, v23
	s_nop 1
	v_mov_b32_dpp v25, v23 row_ror:4 row_mask:0xf bank_mask:0xf
	s_waitcnt lgkmcnt(0)
	v_max_f32_e32 v25, v25, v25
	v_max_f32_e32 v23, v23, v25
	s_nop 1
	v_mov_b32_dpp v25, v23 row_ror:2 row_mask:0xf bank_mask:0xf
	s_waitcnt lgkmcnt(0)
	v_max_f32_e32 v25, v25, v25
	v_max_f32_e32 v23, v23, v25
	s_nop 1
	v_mov_b32_dpp v25, v23 row_ror:1 row_mask:0xf bank_mask:0xf
	s_waitcnt lgkmcnt(0)
	v_max_f32_e32 v25, v25, v25
	v_max_f32_e32 v23, v23, v25
	v_mov_b32_e32 v25, v23
	s_nop 1
	v_permlane16_swap_b32_e32 v23, v25
	v_max_f32_e32 v25, v25, v25
	v_max_f32_e32 v23, v23, v23
	v_max_f32_e32 v23, v23, v25
	v_mov_b32_e32 v25, v23
	s_nop 1
	v_permlane32_swap_b32_e32 v23, v25
	v_max_f32_e32 v25, v25, v25
	v_max_f32_e32 v23, v23, v23
	v_max_f32_e32 v23, v23, v25
	v_cmp_eq_f32_e32 vcc, v20, v23
	s_ff1_i32_b64 s20, vcc
	v_cmp_ne_u32_e32 vcc, s20, v99
	s_lshl_b64 s[20:21], 1, s20
	s_nop 0
	v_cndmask_b32_e32 v20, v242, v20, vcc
	s_nop 1
	v_mov_b32_dpp v23, v20 row_ror:8 row_mask:0xf bank_mask:0xf
	v_max_f32_e32 v25, v20, v20
	s_waitcnt lgkmcnt(0)
	v_max_f32_e32 v23, v23, v23
	v_max_f32_e32 v23, v25, v23
	s_nop 1
	v_mov_b32_dpp v25, v23 row_ror:4 row_mask:0xf bank_mask:0xf
	s_waitcnt lgkmcnt(0)
	v_max_f32_e32 v25, v25, v25
	v_max_f32_e32 v23, v23, v25
	s_nop 1
	v_mov_b32_dpp v25, v23 row_ror:2 row_mask:0xf bank_mask:0xf
	s_waitcnt lgkmcnt(0)
	v_max_f32_e32 v25, v25, v25
	v_max_f32_e32 v23, v23, v25
	s_nop 1
	v_mov_b32_dpp v25, v23 row_ror:1 row_mask:0xf bank_mask:0xf
	s_waitcnt lgkmcnt(0)
	v_max_f32_e32 v25, v25, v25
	v_max_f32_e32 v23, v23, v25
	v_mov_b32_e32 v25, v23
	s_nop 1
	v_permlane16_swap_b32_e32 v23, v25
	v_max_f32_e32 v25, v25, v25
	v_max_f32_e32 v23, v23, v23
	v_max_f32_e32 v23, v23, v25
	v_mov_b32_e32 v25, v23
	s_nop 1
	v_permlane32_swap_b32_e32 v23, v25
	v_max_f32_e32 v25, v25, v25
	v_max_f32_e32 v23, v23, v23
	v_max_f32_e32 v23, v23, v25
	v_cmp_eq_f32_e32 vcc, v20, v23
	s_ff1_i32_b64 s26, vcc
	v_cmp_ne_u32_e32 vcc, s26, v99
	s_lshl_b64 s[26:27], 1, s26
	s_nop 0
	v_cndmask_b32_e32 v20, v242, v20, vcc
	s_nop 1
	v_mov_b32_dpp v23, v20 row_ror:8 row_mask:0xf bank_mask:0xf
	v_max_f32_e32 v25, v20, v20
	s_waitcnt lgkmcnt(0)
	v_max_f32_e32 v23, v23, v23
	v_max_f32_e32 v23, v25, v23
	s_nop 1
	v_mov_b32_dpp v25, v23 row_ror:4 row_mask:0xf bank_mask:0xf
	s_waitcnt lgkmcnt(0)
	v_max_f32_e32 v25, v25, v25
	v_max_f32_e32 v23, v23, v25
	s_nop 1
	v_mov_b32_dpp v25, v23 row_ror:2 row_mask:0xf bank_mask:0xf
	s_waitcnt lgkmcnt(0)
	v_max_f32_e32 v25, v25, v25
	v_max_f32_e32 v23, v23, v25
	s_nop 1
	v_mov_b32_dpp v25, v23 row_ror:1 row_mask:0xf bank_mask:0xf
	s_waitcnt lgkmcnt(0)
	v_max_f32_e32 v25, v25, v25
	v_max_f32_e32 v23, v23, v25
	v_mov_b32_e32 v25, v23
	s_nop 1
	v_permlane16_swap_b32_e32 v23, v25
	v_max_f32_e32 v25, v25, v25
	v_max_f32_e32 v23, v23, v23
	v_max_f32_e32 v23, v23, v25
	v_mov_b32_e32 v25, v23
	s_nop 1
	v_permlane32_swap_b32_e32 v23, v25
	v_max_f32_e32 v25, v25, v25
	v_max_f32_e32 v23, v23, v23
	v_max_f32_e32 v23, v23, v25
	v_cmp_eq_f32_e32 vcc, v20, v23
	s_ff1_i32_b64 s28, vcc
	v_cmp_ne_u32_e32 vcc, s28, v99
	s_lshl_b64 s[28:29], 1, s28
	s_nop 0
	v_cndmask_b32_e32 v20, v242, v20, vcc
	s_nop 1
	v_mov_b32_dpp v22, v20 row_ror:8 row_mask:0xf bank_mask:0xf
	v_max_f32_e32 v23, v20, v20
	s_waitcnt lgkmcnt(0)
	v_max_f32_e32 v22, v22, v22
	v_max_f32_e32 v22, v23, v22
	s_nop 1
	v_mov_b32_dpp v23, v22 row_ror:4 row_mask:0xf bank_mask:0xf
	s_waitcnt lgkmcnt(0)
	v_max_f32_e32 v23, v23, v23
	v_max_f32_e32 v22, v22, v23
	s_nop 1
	v_mov_b32_dpp v23, v22 row_ror:2 row_mask:0xf bank_mask:0xf
	s_waitcnt lgkmcnt(0)
	v_max_f32_e32 v23, v23, v23
	v_max_f32_e32 v22, v22, v23
	s_nop 1
	v_mov_b32_dpp v21, v22 row_ror:1 row_mask:0xf bank_mask:0xf
	s_waitcnt lgkmcnt(0)
	v_max_f32_e32 v21, v21, v21
	v_max_f32_e32 v21, v22, v21
	v_mov_b32_e32 v22, v21
	s_nop 1
	v_permlane16_swap_b32_e32 v21, v22
	v_max_f32_e32 v22, v22, v22
	v_max_f32_e32 v21, v21, v21
	v_max_f32_e32 v21, v21, v22
	v_mov_b32_e32 v22, v21
	s_nop 1
	v_permlane32_swap_b32_e32 v21, v22
	v_max_f32_e32 v22, v22, v22
	v_max_f32_e32 v21, v21, v21
	v_max_f32_e32 v21, v21, v22
	v_cmp_eq_f32_e32 vcc, v20, v21
	s_sub_u32 s30, 0, vcc_lo
	s_subb_u32 s31, 0, vcc_hi
	s_or_b64 s[8:9], s[8:9], s[20:21]
	s_or_b64 s[8:9], s[8:9], s[26:27]
	s_and_b64 s[20:21], vcc, s[30:31]
	s_or_b64 s[8:9], s[8:9], s[28:29]
	s_or_b64 s[8:9], s[8:9], s[20:21]
	s_or_b64 s[8:9], s[8:9], s[0:1]
	s_and_saveexec_b64 s[20:21], s[12:13]
	s_cbranch_execz .LBB0_399

; __device__ __forceinline__ float wave_max(float v) {
; #pragma unroll
;     for (int o = 8; o >= 1; o >>= 1) v = fmaxf(v, __shfl_xor(v, o));
;     return rows_max(v); }
; __device__ __forceinline__ void nsa_unit(LAS unsigned char* lds, const Ctx& P, int l, int b, int hkv, int tb) {
;     ...
;         for (int tt = 0; tt < 8; ++tt) { const int tl = 8 * wid + tt;
;             unsigned long long mask;
;             if (qb <= 7) mask = (2ull << qb) - 1ull;
;             else {
;                 const float v = impb[(0 * 64 + tl) * 64 + lane] + impb[(1 * 64 + tl) * 64 + lane] + impb[(2 * 64 + tl) * 64 + lane] + impb[(3 * 64 + tl) * 64 + lane];
;                 float vv = (lane >= 1 && lane <= qb - 2) ? v : -__builtin_inff();
;                 mask = 1ull | (1ull << qb) | (1ull << (qb - 1));
; #pragma unroll
;                 for (int r = 0; r < 5; ++r) { const float mx = wave_max(vv); const unsigned long long bal = __ballot(vv == mx);
;                     const int js = __builtin_ctzll(bal); mask |= 1ull << js; if (lane == js) vv = -__builtin_inff(); }
;             }
;             if (lane == 0) sels[tl] = mask; }
.LBB0_595:
	s_or_b64 exec, exec, s[4:5]
	v_and_b32_e32 v20, 64, v239
	v_add_u32_e32 v20, 64, v20
	v_xor_b32_e32 v21, 8, v239
	v_cmp_lt_i32_e32 vcc, v21, v20
	v_xor_b32_e32 v23, 4, v239
	v_max_f32_e32 v24, v19, v19
	v_cndmask_b32_e32 v21, v239, v21, vcc
	v_lshlrev_b32_e32 v21, 2, v21
	s_nop 1
	v_mov_b32_dpp v22, v19 row_ror:8 row_mask:0xf bank_mask:0xf
	v_cmp_lt_i32_e32 vcc, v23, v20
	v_xor_b32_e32 v25, 2, v239
	v_xor_b32_e32 v26, 1, v239
	v_cndmask_b32_e32 v23, v239, v23, vcc
	s_waitcnt lgkmcnt(0)
	v_max_f32_e32 v22, v22, v22
	v_lshlrev_b32_e32 v23, 2, v23
	v_max_f32_e32 v22, v24, v22
	s_nop 1
	v_mov_b32_dpp v24, v22 row_ror:4 row_mask:0xf bank_mask:0xf
	v_cmp_lt_i32_e32 vcc, v25, v20
	s_waitcnt lgkmcnt(0)
	v_max_f32_e32 v24, v24, v24
	v_cndmask_b32_e32 v25, v239, v25, vcc
	v_lshlrev_b32_e32 v25, 2, v25
	v_max_f32_e32 v22, v22, v24
	s_nop 1
	v_mov_b32_dpp v24, v22 row_ror:2 row_mask:0xf bank_mask:0xf
	v_cmp_lt_i32_e32 vcc, v26, v20
	s_waitcnt lgkmcnt(0)
	v_max_f32_e32 v24, v24, v24
	v_cndmask_b32_e32 v20, v239, v26, vcc
	v_lshlrev_b32_e32 v20, 2, v20
	v_max_f32_e32 v22, v22, v24
	s_nop 1
	v_mov_b32_dpp v24, v22 row_ror:1 row_mask:0xf bank_mask:0xf
	s_waitcnt lgkmcnt(0)
	v_max_f32_e32 v24, v24, v24
	v_max_f32_e32 v22, v22, v24
	v_mov_b32_e32 v24, v22
	s_nop 1
	v_permlane16_swap_b32_e32 v22, v24
	v_max_f32_e32 v24, v24, v24
	v_max_f32_e32 v22, v22, v22
	v_max_f32_e32 v22, v22, v24
	v_mov_b32_e32 v24, v22
	s_nop 1
	v_permlane32_swap_b32_e32 v22, v24
	v_max_f32_e32 v24, v24, v24
	v_max_f32_e32 v22, v22, v22
	v_max_f32_e32 v22, v22, v24
	v_cmp_eq_f32_e32 vcc, v19, v22
	s_ff1_i32_b64 s4, vcc
	v_cmp_ne_u32_e32 vcc, s4, v99
	s_lshl_b64 s[4:5], 1, s4
	s_nop 0
	v_cndmask_b32_e32 v19, v242, v19, vcc
	s_nop 1
	v_mov_b32_dpp v22, v19 row_ror:8 row_mask:0xf bank_mask:0xf
	v_max_f32_e32 v24, v19, v19
	s_waitcnt lgkmcnt(0)
	v_max_f32_e32 v22, v22, v22
	v_max_f32_e32 v22, v24, v22
	s_nop 1
	v_mov_b32_dpp v24, v22 row_ror:4 row_mask:0xf bank_mask:0xf
	s_waitcnt lgkmcnt(0)
	v_max_f32_e32 v24, v24, v24
	v_max_f32_e32 v22, v22, v24
	s_nop 1
	v_mov_b32_dpp v24, v22 row_ror:2 row_mask:0xf bank_mask:0xf
	s_waitcnt lgkmcnt(0)
	v_max_f32_e32 v24, v24, v24
	v_max_f32_e32 v22, v22, v24
	s_nop 1
	v_mov_b32_dpp v24, v22 row_ror:1 row_mask:0xf bank_mask:0xf
	s_waitcnt lgkmcnt(0)
	v_max_f32_e32 v24, v24, v24
	v_max_f32_e32 v22, v22, v24
	v_mov_b32_e32 v24, v22
	s_nop 1
	v_permlane16_swap_b32_e32 v22, v24
	v_max_f32_e32 v24, v24, v24
	v_max_f32_e32 v22, v22, v22
	v_max_f32_e32 v22, v22, v24
	v_mov_b32_e32 v24, v22
	s_nop 1
	v_permlane32_swap_b32_e32 v22, v24
	v_max_f32_e32 v24, v24, v24
	v_max_f32_e32 v22, v22, v22
	v_max_f32_e32 v22, v22, v24
	v_cmp_eq_f32_e32 vcc, v19, v22
	s_ff1_i32_b64 s8, vcc
	v_cmp_ne_u32_e32 vcc, s8, v99
	s_lshl_b64 s[8:9], 1, s8
	s_nop 0
	v_cndmask_b32_e32 v19, v242, v19, vcc
	s_nop 1
	v_mov_b32_dpp v22, v19 row_ror:8 row_mask:0xf bank_mask:0xf
	v_max_f32_e32 v24, v19, v19
	s_waitcnt lgkmcnt(0)
	v_max_f32_e32 v22, v22, v22
	v_max_f32_e32 v22, v24, v22
	s_nop 1
	v_mov_b32_dpp v24, v22 row_ror:4 row_mask:0xf bank_mask:0xf
	s_waitcnt lgkmcnt(0)
	v_max_f32_e32 v24, v24, v24
	v_max_f32_e32 v22, v22, v24
	s_nop 1
	v_mov_b32_dpp v24, v22 row_ror:2 row_mask:0xf bank_mask:0xf
	s_waitcnt lgkmcnt(0)
	v_max_f32_e32 v24, v24, v24
	v_max_f32_e32 v22, v22, v24
	s_nop 1
	v_mov_b32_dpp v24, v22 row_ror:1 row_mask:0xf bank_mask:0xf
	s_waitcnt lgkmcnt(0)
	v_max_f32_e32 v24, v24, v24
	v_max_f32_e32 v22, v22, v24
	v_mov_b32_e32 v24, v22
	s_nop 1
	v_permlane16_swap_b32_e32 v22, v24
	v_max_f32_e32 v24, v24, v24
	v_max_f32_e32 v22, v22, v22
	v_max_f32_e32 v22, v22, v24
	v_mov_b32_e32 v24, v22
	s_nop 1
	v_permlane32_swap_b32_e32 v22, v24
	v_max_f32_e32 v24, v24, v24
	v_max_f32_e32 v22, v22, v22
	v_max_f32_e32 v22, v22, v24
	v_cmp_eq_f32_e32 vcc, v19, v22
	s_ff1_i32_b64 s14, vcc
	v_cmp_ne_u32_e32 vcc, s14, v99
	s_lshl_b64 s[14:15], 1, s14
	s_nop 0
	v_cndmask_b32_e32 v19, v242, v19, vcc
	s_nop 1
	v_mov_b32_dpp v22, v19 row_ror:8 row_mask:0xf bank_mask:0xf
	v_max_f32_e32 v24, v19, v19
	s_waitcnt lgkmcnt(0)
	v_max_f32_e32 v22, v22, v22
	v_max_f32_e32 v22, v24, v22
	s_nop 1
	v_mov_b32_dpp v24, v22 row_ror:4 row_mask:0xf bank_mask:0xf
	s_waitcnt lgkmcnt(0)
	v_max_f32_e32 v24, v24, v24
	v_max_f32_e32 v22, v22, v24
	s_nop 1
	v_mov_b32_dpp v24, v22 row_ror:2 row_mask:0xf bank_mask:0xf
	s_waitcnt lgkmcnt(0)
	v_max_f32_e32 v24, v24, v24
	v_max_f32_e32 v22, v22, v24
	s_nop 1
	v_mov_b32_dpp v24, v22 row_ror:1 row_mask:0xf bank_mask:0xf
	s_waitcnt lgkmcnt(0)
	v_max_f32_e32 v24, v24, v24
	v_max_f32_e32 v22, v22, v24
	v_mov_b32_e32 v24, v22
	s_nop 1
	v_permlane16_swap_b32_e32 v22, v24
	v_max_f32_e32 v24, v24, v24
	v_max_f32_e32 v22, v22, v22
	v_max_f32_e32 v22, v22, v24
	v_mov_b32_e32 v24, v22
	s_nop 1
	v_permlane32_swap_b32_e32 v22, v24
	v_max_f32_e32 v24, v24, v24
	v_max_f32_e32 v22, v22, v22
	v_max_f32_e32 v22, v22, v24
	v_cmp_eq_f32_e32 vcc, v19, v22
	s_ff1_i32_b64 s16, vcc
	v_cmp_ne_u32_e32 vcc, s16, v99
	s_lshl_b64 s[16:17], 1, s16
	s_nop 0
	v_cndmask_b32_e32 v19, v242, v19, vcc
	s_nop 1
	v_mov_b32_dpp v21, v19 row_ror:8 row_mask:0xf bank_mask:0xf
	v_max_f32_e32 v22, v19, v19
	s_waitcnt lgkmcnt(0)
	v_max_f32_e32 v21, v21, v21
	v_max_f32_e32 v21, v22, v21
	s_nop 1
	v_mov_b32_dpp v22, v21 row_ror:4 row_mask:0xf bank_mask:0xf
	s_waitcnt lgkmcnt(0)
	v_max_f32_e32 v22, v22, v22
	v_max_f32_e32 v21, v21, v22
	s_nop 1
	v_mov_b32_dpp v22, v21 row_ror:2 row_mask:0xf bank_mask:0xf
	s_waitcnt lgkmcnt(0)
	v_max_f32_e32 v22, v22, v22
	v_max_f32_e32 v21, v21, v22
	s_nop 1
	v_mov_b32_dpp v20, v21 row_ror:1 row_mask:0xf bank_mask:0xf
	s_waitcnt lgkmcnt(0)
	v_max_f32_e32 v20, v20, v20
	v_max_f32_e32 v20, v21, v20
	v_mov_b32_e32 v21, v20
	s_nop 1
	v_permlane16_swap_b32_e32 v20, v21
	v_max_f32_e32 v21, v21, v21
	v_max_f32_e32 v20, v20, v20
	v_max_f32_e32 v20, v20, v21
	v_mov_b32_e32 v21, v20
	s_nop 1
	v_permlane32_swap_b32_e32 v20, v21
	v_max_f32_e32 v21, v21, v21
	v_max_f32_e32 v20, v20, v20
	v_max_f32_e32 v20, v20, v21
	v_cmp_eq_f32_e32 vcc, v19, v20
	s_sub_u32 s18, 0, vcc_lo
	s_subb_u32 s19, 0, vcc_hi
	s_or_b64 s[4:5], s[4:5], s[8:9]
	s_or_b64 s[4:5], s[4:5], s[14:15]
	s_and_b64 s[8:9], vcc, s[18:19]
	s_or_b64 s[4:5], s[4:5], s[16:17]
	s_or_b64 s[4:5], s[4:5], s[8:9]
	s_or_b64 s[4:5], s[4:5], s[0:1]
	s_and_saveexec_b64 s[0:1], s[12:13]
	s_cbranch_execnz .LBB0_401
	s_branch .LBB0_402

; __global__ void __launch_bounds__(512, 2) fwd_megakernel(Params PK) {
;     ...
;                 for (size_t idx = gtid; idx < (size_t)2 * 4096 * 256; idx += gstride) { const int ch = (int)(idx & 255), row = (int)((idx >> 8) & 4095), kv = (int)(idx >> 20);
;                     const int j = ch >> 3, d8 = (ch & 7) * 8, bh = row >> 8, n = row & 255, b = bh >> 2, hkv = bh & 3;
;                     u32x4 v = (u32x4){0u, 0u, 0u, 0u};
;                     if (n < 255) v = *(const u32x4*)(Hh + ((size_t)b * SEQ + 16 * n + j) * LDH + (kv ? C_VC : C_KC) + hkv * 64 + d8);
;                     *(u32x4*)(A0 + ((size_t)kv * 4096 + row) * 2048 + j * 64 + d8) = v; } }
.LBB0_846:
.LBB0_847:
	v_and_b32_e32 v6, 56, v7
	s_mov_b64 s[12:13], 0x100000
	v_mov_b64_e32 v[12:13], v[166:167]
	v_lshl_add_u64 v[14:15], v[12:13], 0, s[38:39]
	v_lshl_add_u64 v[16:17], v[14:15], 0, s[38:39]
	v_lshl_add_u64 v[18:19], v[16:17], 0, s[38:39]
	v_lshl_add_u64 v[20:21], v[18:19], 0, s[38:39]
	v_lshl_add_u64 v[22:23], v[20:21], 0, s[38:39]
	v_lshl_add_u64 v[24:25], v[22:23], 0, s[38:39]
	v_lshl_add_u64 v[26:27], v[24:25], 0, s[38:39]
	v_mov_b32_e32 v28, 0
	v_mov_b32_e32 v29, 0
	v_mov_b32_e32 v30, 0
	v_mov_b32_e32 v31, 0
	v_bfe_u32 v0, v12, 8, 8
	v_cmp_ne_u32_e32 vcc, 0xff, v0
	s_and_saveexec_b64 s[8:9], vcc
	v_lshrrev_b32_e32 v9, 8, v12
	v_bfe_u32 v8, v12, 3, 5
	v_lshlrev_b32_e32 v2, 4, v0
	v_lshlrev_b32_e32 v0, 2, v9
	v_and_b32_e32 v0, 0x3000, v0
	v_add3_u32 v0, v2, v8, v0
	v_mul_u32_u24_e32 v0, 0x2b00, v0
	v_lshlrev_b32_e32 v0, 1, v0
	v_lshl_add_u64 v[2:3], s[10:11], 0, v[0:1]
	v_cmp_gt_u64_e32 vcc, s[12:13], v[12:13]
	v_mov_b32_e32 v0, 0x3200
	v_mov_b32_e32 v4, 0x3000
	v_cndmask_b32_e32 v0, v0, v4, vcc
	v_lshl_add_u64 v[2:3], v[2:3], 0, v[0:1]
	v_lshrrev_b32_e32 v0, 9, v12
	v_and_b32_e32 v0, 0x180, v0
	v_lshl_add_u64 v[2:3], v[2:3], 0, v[0:1]
	v_lshlrev_b32_e32 v0, 1, v6
	v_lshl_add_u64 v[2:3], v[2:3], 0, v[0:1]
	global_load_dwordx4 v[28:31], v[2:3], off
	s_or_b64 exec, exec, s[8:9]
	v_mov_b32_e32 v32, 0
	v_mov_b32_e32 v33, 0
	v_mov_b32_e32 v34, 0
	v_mov_b32_e32 v35, 0
	v_bfe_u32 v0, v14, 8, 8
	v_cmp_ne_u32_e32 vcc, 0xff, v0
	s_and_saveexec_b64 s[8:9], vcc
	v_lshrrev_b32_e32 v9, 8, v14
	v_bfe_u32 v8, v14, 3, 5
	v_lshlrev_b32_e32 v2, 4, v0
	v_lshlrev_b32_e32 v0, 2, v9
	v_and_b32_e32 v0, 0x3000, v0
	v_add3_u32 v0, v2, v8, v0
	v_mul_u32_u24_e32 v0, 0x2b00, v0
	v_lshlrev_b32_e32 v0, 1, v0
	v_lshl_add_u64 v[2:3], s[10:11], 0, v[0:1]
	v_cmp_gt_u64_e32 vcc, s[12:13], v[14:15]
	v_mov_b32_e32 v0, 0x3200
	v_mov_b32_e32 v4, 0x3000
	v_cndmask_b32_e32 v0, v0, v4, vcc
	v_lshl_add_u64 v[2:3], v[2:3], 0, v[0:1]
	v_lshrrev_b32_e32 v0, 9, v14
	v_and_b32_e32 v0, 0x180, v0
	v_lshl_add_u64 v[2:3], v[2:3], 0, v[0:1]
	v_lshlrev_b32_e32 v0, 1, v6
	v_lshl_add_u64 v[2:3], v[2:3], 0, v[0:1]
	global_load_dwordx4 v[32:35], v[2:3], off
	s_or_b64 exec, exec, s[8:9]
	v_mov_b32_e32 v36, 0
	v_mov_b32_e32 v37, 0
	v_mov_b32_e32 v38, 0
	v_mov_b32_e32 v39, 0
	v_bfe_u32 v0, v16, 8, 8
	v_cmp_ne_u32_e32 vcc, 0xff, v0
	s_and_saveexec_b64 s[8:9], vcc
	v_lshrrev_b32_e32 v9, 8, v16
	v_bfe_u32 v8, v16, 3, 5
	v_lshlrev_b32_e32 v2, 4, v0
	v_lshlrev_b32_e32 v0, 2, v9
	v_and_b32_e32 v0, 0x3000, v0
	v_add3_u32 v0, v2, v8, v0
	v_mul_u32_u24_e32 v0, 0x2b00, v0
	v_lshlrev_b32_e32 v0, 1, v0
	v_lshl_add_u64 v[2:3], s[10:11], 0, v[0:1]
	v_cmp_gt_u64_e32 vcc, s[12:13], v[16:17]
	v_mov_b32_e32 v0, 0x3200
	v_mov_b32_e32 v4, 0x3000
	v_cndmask_b32_e32 v0, v0, v4, vcc
	v_lshl_add_u64 v[2:3], v[2:3], 0, v[0:1]
	v_lshrrev_b32_e32 v0, 9, v16
	v_and_b32_e32 v0, 0x180, v0
	v_lshl_add_u64 v[2:3], v[2:3], 0, v[0:1]
	v_lshlrev_b32_e32 v0, 1, v6
	v_lshl_add_u64 v[2:3], v[2:3], 0, v[0:1]
	global_load_dwordx4 v[36:39], v[2:3], off
	s_or_b64 exec, exec, s[8:9]
	v_mov_b32_e32 v40, 0
	v_mov_b32_e32 v41, 0
	v_mov_b32_e32 v42, 0
	v_mov_b32_e32 v43, 0
	v_bfe_u32 v0, v18, 8, 8
	v_cmp_ne_u32_e32 vcc, 0xff, v0
	s_and_saveexec_b64 s[8:9], vcc
	v_lshrrev_b32_e32 v9, 8, v18
	v_bfe_u32 v8, v18, 3, 5
	v_lshlrev_b32_e32 v2, 4, v0
	v_lshlrev_b32_e32 v0, 2, v9
	v_and_b32_e32 v0, 0x3000, v0
	v_add3_u32 v0, v2, v8, v0
	v_mul_u32_u24_e32 v0, 0x2b00, v0
	v_lshlrev_b32_e32 v0, 1, v0
	v_lshl_add_u64 v[2:3], s[10:11], 0, v[0:1]
	v_cmp_gt_u64_e32 vcc, s[12:13], v[18:19]
	v_mov_b32_e32 v0, 0x3200
	v_mov_b32_e32 v4, 0x3000
	v_cndmask_b32_e32 v0, v0, v4, vcc
	v_lshl_add_u64 v[2:3], v[2:3], 0, v[0:1]
	v_lshrrev_b32_e32 v0, 9, v18
	v_and_b32_e32 v0, 0x180, v0
	v_lshl_add_u64 v[2:3], v[2:3], 0, v[0:1]
	v_lshlrev_b32_e32 v0, 1, v6
	v_lshl_add_u64 v[2:3], v[2:3], 0, v[0:1]
	global_load_dwordx4 v[40:43], v[2:3], off
	s_or_b64 exec, exec, s[8:9]
	v_mov_b32_e32 v44, 0
	v_mov_b32_e32 v45, 0
	v_mov_b32_e32 v46, 0
	v_mov_b32_e32 v47, 0
	v_bfe_u32 v0, v20, 8, 8
	v_cmp_ne_u32_e32 vcc, 0xff, v0
	s_and_saveexec_b64 s[8:9], vcc
	v_lshrrev_b32_e32 v9, 8, v20
	v_bfe_u32 v8, v20, 3, 5
	v_lshlrev_b32_e32 v2, 4, v0
	v_lshlrev_b32_e32 v0, 2, v9
	v_and_b32_e32 v0, 0x3000, v0
	v_add3_u32 v0, v2, v8, v0
	v_mul_u32_u24_e32 v0, 0x2b00, v0
	v_lshlrev_b32_e32 v0, 1, v0
	v_lshl_add_u64 v[2:3], s[10:11], 0, v[0:1]
	v_cmp_gt_u64_e32 vcc, s[12:13], v[20:21]
	v_mov_b32_e32 v0, 0x3200
	v_mov_b32_e32 v4, 0x3000
	v_cndmask_b32_e32 v0, v0, v4, vcc
	v_lshl_add_u64 v[2:3], v[2:3], 0, v[0:1]
	v_lshrrev_b32_e32 v0, 9, v20
	v_and_b32_e32 v0, 0x180, v0
	v_lshl_add_u64 v[2:3], v[2:3], 0, v[0:1]
	v_lshlrev_b32_e32 v0, 1, v6
	v_lshl_add_u64 v[2:3], v[2:3], 0, v[0:1]
	global_load_dwordx4 v[44:47], v[2:3], off
	s_or_b64 exec, exec, s[8:9]
	v_mov_b32_e32 v48, 0
	v_mov_b32_e32 v49, 0
	v_mov_b32_e32 v50, 0
	v_mov_b32_e32 v51, 0
	v_bfe_u32 v0, v22, 8, 8
	v_cmp_ne_u32_e32 vcc, 0xff, v0
	s_and_saveexec_b64 s[8:9], vcc
	v_lshrrev_b32_e32 v9, 8, v22
	v_bfe_u32 v8, v22, 3, 5
	v_lshlrev_b32_e32 v2, 4, v0
	v_lshlrev_b32_e32 v0, 2, v9
	v_and_b32_e32 v0, 0x3000, v0
	v_add3_u32 v0, v2, v8, v0
	v_mul_u32_u24_e32 v0, 0x2b00, v0
	v_lshlrev_b32_e32 v0, 1, v0
	v_lshl_add_u64 v[2:3], s[10:11], 0, v[0:1]
	v_cmp_gt_u64_e32 vcc, s[12:13], v[22:23]
; __global__ void __launch_bounds__(512, 2) fwd_megakernel(Params PK) {
;     ...
;                 for (size_t idx = gtid; idx < (size_t)2 * 4096 * 256; idx += gstride) { const int ch = (int)(idx & 255), row = (int)((idx >> 8) & 4095), kv = (int)(idx >> 20);
;                     const int j = ch >> 3, d8 = (ch & 7) * 8, bh = row >> 8, n = row & 255, b = bh >> 2, hkv = bh & 3;
;                     u32x4 v = (u32x4){0u, 0u, 0u, 0u};
;                     if (n < 255) v = *(const u32x4*)(Hh + ((size_t)b * SEQ + 16 * n + j) * LDH + (kv ? C_VC : C_KC) + hkv * 64 + d8);
;                     *(u32x4*)(A0 + ((size_t)kv * 4096 + row) * 2048 + j * 64 + d8) = v; } }
	v_mov_b32_e32 v0, 0x3200
	v_mov_b32_e32 v4, 0x3000
	v_cndmask_b32_e32 v0, v0, v4, vcc
	v_lshl_add_u64 v[2:3], v[2:3], 0, v[0:1]
	v_lshrrev_b32_e32 v0, 9, v22
	v_and_b32_e32 v0, 0x180, v0
	v_lshl_add_u64 v[2:3], v[2:3], 0, v[0:1]
	v_lshlrev_b32_e32 v0, 1, v6
	v_lshl_add_u64 v[2:3], v[2:3], 0, v[0:1]
	global_load_dwordx4 v[48:51], v[2:3], off
	s_or_b64 exec, exec, s[8:9]
	v_mov_b32_e32 v52, 0
	v_mov_b32_e32 v53, 0
	v_mov_b32_e32 v54, 0
	v_mov_b32_e32 v55, 0
	v_bfe_u32 v0, v24, 8, 8
	v_cmp_ne_u32_e32 vcc, 0xff, v0
	s_and_saveexec_b64 s[8:9], vcc
	v_lshrrev_b32_e32 v9, 8, v24
	v_bfe_u32 v8, v24, 3, 5
	v_lshlrev_b32_e32 v2, 4, v0
	v_lshlrev_b32_e32 v0, 2, v9
	v_and_b32_e32 v0, 0x3000, v0
	v_add3_u32 v0, v2, v8, v0
	v_mul_u32_u24_e32 v0, 0x2b00, v0
	v_lshlrev_b32_e32 v0, 1, v0
	v_lshl_add_u64 v[2:3], s[10:11], 0, v[0:1]
	v_cmp_gt_u64_e32 vcc, s[12:13], v[24:25]
	v_mov_b32_e32 v0, 0x3200
	v_mov_b32_e32 v4, 0x3000
	v_cndmask_b32_e32 v0, v0, v4, vcc
	v_lshl_add_u64 v[2:3], v[2:3], 0, v[0:1]
	v_lshrrev_b32_e32 v0, 9, v24
	v_and_b32_e32 v0, 0x180, v0
	v_lshl_add_u64 v[2:3], v[2:3], 0, v[0:1]
	v_lshlrev_b32_e32 v0, 1, v6
	v_lshl_add_u64 v[2:3], v[2:3], 0, v[0:1]
	global_load_dwordx4 v[52:55], v[2:3], off
	s_or_b64 exec, exec, s[8:9]
	v_mov_b32_e32 v56, 0
	v_mov_b32_e32 v57, 0
	v_mov_b32_e32 v58, 0
	v_mov_b32_e32 v59, 0
	v_bfe_u32 v0, v26, 8, 8
	v_cmp_ne_u32_e32 vcc, 0xff, v0
	s_and_saveexec_b64 s[8:9], vcc
	v_lshrrev_b32_e32 v9, 8, v26
	v_bfe_u32 v8, v26, 3, 5
	v_lshlrev_b32_e32 v2, 4, v0
	v_lshlrev_b32_e32 v0, 2, v9
	v_and_b32_e32 v0, 0x3000, v0
	v_add3_u32 v0, v2, v8, v0
	v_mul_u32_u24_e32 v0, 0x2b00, v0
	v_lshlrev_b32_e32 v0, 1, v0
	v_lshl_add_u64 v[2:3], s[10:11], 0, v[0:1]
	v_cmp_gt_u64_e32 vcc, s[12:13], v[26:27]
	v_mov_b32_e32 v0, 0x3200
	v_mov_b32_e32 v4, 0x3000
	v_cndmask_b32_e32 v0, v0, v4, vcc
	v_lshl_add_u64 v[2:3], v[2:3], 0, v[0:1]
	v_lshrrev_b32_e32 v0, 9, v26
	v_and_b32_e32 v0, 0x180, v0
	v_lshl_add_u64 v[2:3], v[2:3], 0, v[0:1]
	v_lshlrev_b32_e32 v0, 1, v6
	v_lshl_add_u64 v[2:3], v[2:3], 0, v[0:1]
	global_load_dwordx4 v[56:59], v[2:3], off
	s_or_b64 exec, exec, s[8:9]
	v_lshrrev_b32_e32 v9, 8, v12
	v_and_b32_e32 v0, 0x1fff, v9
	v_lshlrev_b32_e32 v0, 12, v0
	v_lshl_add_u64 v[10:11], s[4:5], 0, v[0:1]
	v_bfe_u32 v8, v12, 3, 5
	v_lshlrev_b32_e32 v0, 7, v8
	v_lshl_add_u64 v[8:9], v[10:11], 0, v[0:1]
	v_lshlrev_b32_e32 v0, 1, v6
	v_lshl_add_u64 v[8:9], v[8:9], 0, v[0:1]
	s_waitcnt vmcnt(7)
	global_store_dwordx4 v[8:9], v[28:31], off
	v_lshrrev_b32_e32 v9, 8, v14
	v_and_b32_e32 v0, 0x1fff, v9
	v_lshlrev_b32_e32 v0, 12, v0
	v_lshl_add_u64 v[10:11], s[4:5], 0, v[0:1]
	v_bfe_u32 v8, v14, 3, 5
	v_lshlrev_b32_e32 v0, 7, v8
	v_lshl_add_u64 v[8:9], v[10:11], 0, v[0:1]
	v_lshlrev_b32_e32 v0, 1, v6
	v_lshl_add_u64 v[8:9], v[8:9], 0, v[0:1]
	s_waitcnt vmcnt(7)
	global_store_dwordx4 v[8:9], v[32:35], off
	v_lshrrev_b32_e32 v9, 8, v16
	v_and_b32_e32 v0, 0x1fff, v9
	v_lshlrev_b32_e32 v0, 12, v0
	v_lshl_add_u64 v[10:11], s[4:5], 0, v[0:1]
	v_bfe_u32 v8, v16, 3, 5
	v_lshlrev_b32_e32 v0, 7, v8
	v_lshl_add_u64 v[8:9], v[10:11], 0, v[0:1]
	v_lshlrev_b32_e32 v0, 1, v6
	v_lshl_add_u64 v[8:9], v[8:9], 0, v[0:1]
	s_waitcnt vmcnt(7)
	global_store_dwordx4 v[8:9], v[36:39], off
	v_lshrrev_b32_e32 v9, 8, v18
	v_and_b32_e32 v0, 0x1fff, v9
	v_lshlrev_b32_e32 v0, 12, v0
	v_lshl_add_u64 v[10:11], s[4:5], 0, v[0:1]
	v_bfe_u32 v8, v18, 3, 5
	v_lshlrev_b32_e32 v0, 7, v8
	v_lshl_add_u64 v[8:9], v[10:11], 0, v[0:1]
	v_lshlrev_b32_e32 v0, 1, v6
	v_lshl_add_u64 v[8:9], v[8:9], 0, v[0:1]
	s_waitcnt vmcnt(7)
	global_store_dwordx4 v[8:9], v[40:43], off
	v_lshrrev_b32_e32 v9, 8, v20
	v_and_b32_e32 v0, 0x1fff, v9
	v_lshlrev_b32_e32 v0, 12, v0
	v_lshl_add_u64 v[10:11], s[4:5], 0, v[0:1]
	v_bfe_u32 v8, v20, 3, 5
	v_lshlrev_b32_e32 v0, 7, v8
	v_lshl_add_u64 v[8:9], v[10:11], 0, v[0:1]
	v_lshlrev_b32_e32 v0, 1, v6
	v_lshl_add_u64 v[8:9], v[8:9], 0, v[0:1]
	s_waitcnt vmcnt(7)
	global_store_dwordx4 v[8:9], v[44:47], off
	v_lshrrev_b32_e32 v9, 8, v22
	v_and_b32_e32 v0, 0x1fff, v9
	v_lshlrev_b32_e32 v0, 12, v0
	v_lshl_add_u64 v[10:11], s[4:5], 0, v[0:1]
	v_bfe_u32 v8, v22, 3, 5
	v_lshlrev_b32_e32 v0, 7, v8
	v_lshl_add_u64 v[8:9], v[10:11], 0, v[0:1]
	v_lshlrev_b32_e32 v0, 1, v6
	v_lshl_add_u64 v[8:9], v[8:9], 0, v[0:1]
	s_waitcnt vmcnt(7)
	global_store_dwordx4 v[8:9], v[48:51], off
	v_lshrrev_b32_e32 v9, 8, v24
	v_and_b32_e32 v0, 0x1fff, v9
	v_lshlrev_b32_e32 v0, 12, v0
	v_lshl_add_u64 v[10:11], s[4:5], 0, v[0:1]
	v_bfe_u32 v8, v24, 3, 5
	v_lshlrev_b32_e32 v0, 7, v8
	v_lshl_add_u64 v[8:9], v[10:11], 0, v[0:1]
	v_lshlrev_b32_e32 v0, 1, v6
	v_lshl_add_u64 v[8:9], v[8:9], 0, v[0:1]
	s_waitcnt vmcnt(7)
	global_store_dwordx4 v[8:9], v[52:55], off
	v_lshrrev_b32_e32 v9, 8, v26
	v_and_b32_e32 v0, 0x1fff, v9
	v_lshlrev_b32_e32 v0, 12, v0
	v_lshl_add_u64 v[10:11], s[4:5], 0, v[0:1]
	v_bfe_u32 v8, v26, 3, 5
	v_lshlrev_b32_e32 v0, 7, v8
	v_lshl_add_u64 v[8:9], v[10:11], 0, v[0:1]
	v_lshlrev_b32_e32 v0, 1, v6
	v_lshl_add_u64 v[8:9], v[8:9], 0, v[0:1]
	s_waitcnt vmcnt(7)
	global_store_dwordx4 v[8:9], v[56:59], off
	v_lshl_add_u64 v[166:167], v[26:27], 0, s[38:39]
	s_mov_b64 s[8:9], 0x1fffff
	v_cmp_lt_u64_e32 vcc, s[8:9], v[166:167]
	s_or_b64 s[6:7], vcc, s[6:7]
	s_andn2_b64 exec, exec, s[6:7]
	s_cbranch_execnz .LBB0_847

; __device__ __forceinline__ void tconv_tile(LAS float* tile, const float* src, int ld, int k0, int n0, int mode, bf16_t* dst, int K) {
;     const int tid = opaque_tid();
; #pragma unroll
;     for (int it = 0; it < 2; ++it) { const int idx = tid + it * 512, kk = idx >> 4, n4 = (idx & 15) * 4, nn = n0 + n4; int oc = nn; bool valid = true;
;         if (mode == 1) { if (nn < 7680) oc = nn; else if (nn < 18944) oc = nn + 48; else if (nn < INW) oc = 7680 + (nn - 18944); else valid = false; }
;         f32x4 v = (f32x4){0.f, 0.f, 0.f, 0.f}; if (valid) v = *(const f32x4*)(src + (size_t)(k0 + kk) * ld + oc);
; __device__ __forceinline__ void prologue(LAS unsigned char* lds, const Ctx& P, int l) {
;     ...
;     const int T_IN = 32 * 300, T_BR = 4 * 512, T_OUT = 1024, T_MEM = 1024, T_W1 = 256, T_WA = 64;
;     const int T_ALL = T_IN + T_BR + T_OUT + T_MEM + T_W1 + T_WA;
;     for (int t = blockIdx.x; t < T_ALL; t += G) {
;         int q = t;
;         if (q < T_IN) { const int kt = q & 31, ntl = q >> 5; tconv_tile(tile, P.in[3] + (size_t)l * DM * INW, INW, kt * 64, ntl * 64, 1, (bf16_t*)(ws + WS_WIN), DM); continue; }
;         q -= T_IN;
;         if (q < T_BR) { const int br = q >> 9, r = q & 511, kt = r & 15, ntl = r >> 4;
;             tconv_tile(tile, P.in[23] + ((size_t)l * 4 + br) * DBR * DM, DM, kt * 64, ntl * 64, 0, (bf16_t*)(ws + WS_WBR) + (size_t)br * DM * DBR, DBR); continue; }
;         q -= T_BR;
;         if (q < T_OUT) { const int kt = q & 31, ntl = q >> 5; tconv_tile(tile, P.in[24] + (size_t)l * DM * DM, DM, kt * 64, ntl * 64, 0, (bf16_t*)(ws + WS_WOUT), DM); continue; }
;         q -= T_OUT;
;         if (q < T_MEM) { const int kt = q & 31, ntl = q >> 5; tconv_tile(tile, P.in[22] + (size_t)l * DM * DM, DM, kt * 64, ntl * 64, 0, (bf16_t*)(ws + WS_WMEM), DM); continue; }
;         q -= T_MEM;
;         if (q < T_W1) { const int kv = q >> 7, r = q & 127, kt = r & 31, ntl = r >> 5;
;             tconv_tile(tile, P.in[17 + kv] + (size_t)l * 2048 * 256, 256, kt * 64, ntl * 64, 0, (bf16_t*)(ws + WS_W1T) + (size_t)kv * 256 * 2048, 2048); continue; }
;         q -= T_W1;
;         { const int mat = q >> 5, r = q & 31, n = r >> 2, kt = r & 1, ntl = (r >> 1) & 1;
;             tconv_tile(tile, P.in[mat ? 12 : 10] + ((size_t)l * 8 + n) * 128 * 128, 128, kt * 64, ntl * 64, 0, (bf16_t*)(ws + WS_WAT) + ((size_t)mat * 8 + n) * 128 * 128, 128); }
;     }
.LBB0_868:
	v_mov_b32_e32 v26, 0x23f00
	ds_read_b64 v[34:35], v26 offset:24
	ds_read_b64 v[36:37], v26 offset:184
	ds_read_b64 v[38:39], v26 offset:192
	ds_read_b64 v[40:41], v26 offset:176
	ds_read_b64 v[42:43], v26 offset:136
	ds_read_b64 v[44:45], v26 offset:144
	ds_read_b64 v[46:47], v26 offset:80
	ds_read_b64 v[48:49], v26 offset:96
	s_waitcnt lgkmcnt(0)
	v_readfirstlane_b32 s4, v34
	v_readfirstlane_b32 s5, v35
	v_readfirstlane_b32 s6, v36
	v_readfirstlane_b32 s7, v37
	v_readfirstlane_b32 s8, v38
	v_readfirstlane_b32 s9, v39
	v_readfirstlane_b32 s10, v40
	v_readfirstlane_b32 s11, v41
	v_readfirstlane_b32 s12, v42
	v_readfirstlane_b32 s13, v43
	v_readfirstlane_b32 s14, v44
	v_readfirstlane_b32 s15, v45
	v_readfirstlane_b32 s16, v46
	v_readfirstlane_b32 s17, v47
	v_readfirstlane_b32 s18, v48
	v_readfirstlane_b32 s19, v49
	s_nop 3
	s_add_u32 s4, s4, 0x9460000
	s_addc_u32 s5, s5, 0
	s_add_u32 s6, s6, 0x2000000
	s_addc_u32 s7, s7, 0
	s_add_u32 s8, s8, 0x1000000
	s_addc_u32 s9, s9, 0
	s_add_u32 s10, s10, 0x1000000
	s_addc_u32 s11, s11, 0
	s_add_u32 s12, s12, 0x200000
	s_addc_u32 s13, s13, 0
	s_add_u32 s14, s14, 0x200000
	s_addc_u32 s15, s15, 0
	s_add_u32 s16, s16, 0x80000
	s_addc_u32 s17, s17, 0
	s_add_u32 s18, s18, 0x80000
	s_addc_u32 s19, s19, 0
	v_lshrrev_b32_e32 v20, 4, v234
	v_and_b32_e32 v21, 15, v234
	v_lshlrev_b32_e32 v21, 2, v21
	v_mul_u32_u24_e32 v22, 0x104, v20
	v_lshl_add_u32 v22, v21, 2, v22
	v_lshrrev_b32_e32 v24, 3, v234
	v_and_b32_e32 v25, 7, v234
	v_lshlrev_b32_e32 v25, 3, v25
	v_mul_u32_u24_e32 v23, 0x104, v25
	v_lshl_add_u32 v23, v24, 2, v23
	s_mov_b32 s24, s2
	s_mov_b32 s25, s2
	s_min_u32 s0, s24, 14015
	s_mov_b32 s21, s0
	s_mov_b32 s0, s21
	s_cmpk_lt_u32 s0, 9600
	s_cbranch_scc0 .Ltc1_c2
	s_and_b32 s1, s0, 31
	s_lshl_b32 s1, s1, 6
	s_lshr_b32 s21, s0, 5
	s_lshl_b32 s21, s21, 6
	s_movk_i32 s29, 64
	s_cmpk_lt_u32 s21, 7680
	s_cbranch_scc1 .Ltc1_n4
	s_cmpk_lt_u32 s21, 18944
	s_cbranch_scc0 .Ltc1_t3
	s_add_u32 s21, s21, 48
	s_branch .Ltc1_n4
.Ltc1_t3:
	s_sub_u32 s21, s21, 18944
	s_sub_i32 s29, 48, s21
	s_add_u32 s21, s21, 7680
.Ltc1_n4:
	s_mul_i32 s1, s1, 18992
	s_add_u32 s1, s1, s21
	s_lshl_b32 s1, s1, 2
	s_add_u32 s26, s4, s1
	s_addc_u32 s27, s5, 0
	s_mov_b32 s28, 18992
	s_branch .Ltc1_d1
.Ltc1_c2:
	s_sub_u32 s0, s0, 9600
	s_cmpk_lt_u32 s0, 2048
	s_cbranch_scc0 .Ltc1_c5
	s_lshr_b32 s21, s0, 9
	s_and_b32 s1, s0, 15
	s_lshl_b32 s1, s1, 17
	s_bfe_u32 s29, s0, 0x50004
	s_lshl_b32 s29, s29, 6
	s_add_u32 s1, s1, s29
	s_lshl_b32 s1, s1, 2
	s_lshl_b32 s21, s21, 23
	s_add_u32 s1, s1, s21
	s_add_u32 s26, s6, s1
	s_addc_u32 s27, s7, 0
	s_movk_i32 s28, 0x800
	s_movk_i32 s29, 64
	s_branch .Ltc1_d1
.Ltc1_c5:
	s_sub_u32 s0, s0, 2048
	s_cmpk_lt_u32 s0, 1024
	s_cbranch_scc0 .Ltc1_c6
	s_and_b32 s1, s0, 31
	s_lshl_b32 s1, s1, 17
	s_lshr_b32 s21, s0, 5
	s_lshl_b32 s21, s21, 6
	s_add_u32 s1, s1, s21
	s_lshl_b32 s1, s1, 2
	s_add_u32 s26, s8, s1
	s_addc_u32 s27, s9, 0
	s_movk_i32 s28, 0x800
	s_movk_i32 s29, 64
	s_branch .Ltc1_d1
.Ltc1_c6:
	s_sub_u32 s0, s0, 1024
	s_cmpk_lt_u32 s0, 1024
	s_cbranch_scc0 .Ltc1_c7
	s_and_b32 s1, s0, 31
	s_lshl_b32 s1, s1, 17
	s_lshr_b32 s21, s0, 5
	s_lshl_b32 s21, s21, 6
	s_add_u32 s1, s1, s21
	s_lshl_b32 s1, s1, 2
	s_add_u32 s26, s10, s1
	s_addc_u32 s27, s11, 0
	s_movk_i32 s28, 0x800
	s_movk_i32 s29, 64
	s_branch .Ltc1_d1
.Ltc1_c7:
	s_sub_u32 s0, s0, 1024
	s_cmpk_lt_u32 s0, 256
	s_cbranch_scc0 .Ltc1_c8
	s_and_b32 s1, s0, 31
	s_lshl_b32 s1, s1, 14
	s_bfe_u32 s21, s0, 0x20005
	s_lshl_b32 s21, s21, 6
	s_add_u32 s1, s1, s21
	s_lshl_b32 s1, s1, 2
	s_bitcmp1_b32 s0, 7
	s_cbranch_scc1 .Ltc1_w9
	s_add_u32 s26, s12, s1
	s_addc_u32 s27, s13, 0
	s_branch .Ltc1_n10
.Ltc1_w9:
	s_add_u32 s26, s14, s1
	s_addc_u32 s27, s15, 0
.Ltc1_n10:
	s_movk_i32 s28, 0x100
	s_movk_i32 s29, 64
	s_branch .Ltc1_d1
.Ltc1_c8:
	s_sub_u32 s0, s0, 256
	s_and_b32 s1, s0, 1
	s_lshl_b32 s1, s1, 13
	s_bfe_u32 s21, s0, 0x10001
	s_lshl_b32 s21, s21, 6
	s_add_u32 s1, s1, s21
	s_lshl_b32 s1, s1, 2
	s_bfe_u32 s21, s0, 0x30002
	s_lshl_b32 s21, s21, 16
	s_add_u32 s1, s1, s21
	s_bitcmp1_b32 s0, 5
	s_cbranch_scc1 .Ltc1_w12
	s_add_u32 s26, s16, s1
	s_addc_u32 s27, s17, 0
	s_branch .Ltc1_n13
.Ltc1_w12:
	s_add_u32 s26, s18, s1
	s_addc_u32 s27, s19, 0
.Ltc1_n13:
	s_movk_i32 s28, 0x80
	s_movk_i32 s29, 64
.Ltc1_d1:
	v_mov_b32_e32 v34, 0
	v_mov_b32_e32 v35, 0
	v_mov_b32_e32 v36, 0
	v_mov_b32_e32 v37, 0
	v_mov_b32_e32 v38, 0
	v_mov_b32_e32 v39, 0
	v_mov_b32_e32 v40, 0
	v_mov_b32_e32 v41, 0
	v_mul_u32_u24_e32 v26, s28, v20
	v_add_lshl_u32 v26, v26, v21, 2
	s_lshl_b32 s0, s28, 7
	v_add_u32_e32 v27, s0, v26
	v_cmp_gt_i32_e32 vcc, s29, v21
	s_and_saveexec_b64 s[0:1], vcc
	global_load_dwordx4 v[34:37], v26, s[26:27]
	global_load_dwordx4 v[38:41], v27, s[26:27]
	s_mov_b64 exec, s[0:1]
	s_add_u32 s24, s24, s34
	s_min_u32 s0, s24, 14015
	s_mov_b32 s21, s0
	s_mov_b32 s0, s21
	s_cmpk_lt_u32 s0, 9600
	s_cbranch_scc0 .Ltc1_c15
	s_and_b32 s1, s0, 31
	s_lshl_b32 s1, s1, 6
	s_lshr_b32 s21, s0, 5
	s_lshl_b32 s21, s21, 6
	s_movk_i32 s29, 64
	s_cmpk_lt_u32 s21, 7680
	s_cbranch_scc1 .Ltc1_n17
	s_cmpk_lt_u32 s21, 18944
	s_cbranch_scc0 .Ltc1_t16
	s_add_u32 s21, s21, 48
	s_branch .Ltc1_n17

; __device__ __forceinline__ void tconv_tile(LAS float* tile, const float* src, int ld, int k0, int n0, int mode, bf16_t* dst, int K) {
;     ...
;     for (int it = 0; it < 2; ++it) { const int idx = tid + it * 512, kk = idx >> 4, n4 = (idx & 15) * 4, nn = n0 + n4; int oc = nn; bool valid = true;
;         if (mode == 1) { if (nn < 7680) oc = nn; else if (nn < 18944) oc = nn + 48; else if (nn < INW) oc = 7680 + (nn - 18944); else valid = false; }
;         f32x4 v = (f32x4){0.f, 0.f, 0.f, 0.f}; if (valid) v = *(const f32x4*)(src + (size_t)(k0 + kk) * ld + oc);
; __device__ __forceinline__ void prologue(LAS unsigned char* lds, const Ctx& P, int l) {
;     ...
;     for (int t = blockIdx.x; t < T_ALL; t += G) {
;         int q = t;
;         if (q < T_IN) { const int kt = q & 31, ntl = q >> 5; tconv_tile(tile, P.in[3] + (size_t)l * DM * INW, INW, kt * 64, ntl * 64, 1, (bf16_t*)(ws + WS_WIN), DM); continue; }
;         q -= T_IN;
;         if (q < T_BR) { const int br = q >> 9, r = q & 511, kt = r & 15, ntl = r >> 4;
;             tconv_tile(tile, P.in[23] + ((size_t)l * 4 + br) * DBR * DM, DM, kt * 64, ntl * 64, 0, (bf16_t*)(ws + WS_WBR) + (size_t)br * DM * DBR, DBR); continue; }
;         q -= T_BR;
;         if (q < T_OUT) { const int kt = q & 31, ntl = q >> 5; tconv_tile(tile, P.in[24] + (size_t)l * DM * DM, DM, kt * 64, ntl * 64, 0, (bf16_t*)(ws + WS_WOUT), DM); continue; }
;         q -= T_OUT;
;         if (q < T_MEM) { const int kt = q & 31, ntl = q >> 5; tconv_tile(tile, P.in[22] + (size_t)l * DM * DM, DM, kt * 64, ntl * 64, 0, (bf16_t*)(ws + WS_WMEM), DM); continue; }
;         q -= T_MEM;
;         if (q < T_W1) { const int kv = q >> 7, r = q & 127, kt = r & 31, ntl = r >> 5;
;             tconv_tile(tile, P.in[17 + kv] + (size_t)l * 2048 * 256, 256, kt * 64, ntl * 64, 0, (bf16_t*)(ws + WS_W1T) + (size_t)kv * 256 * 2048, 2048); continue; }
;         q -= T_W1;
;         { const int mat = q >> 5, r = q & 31, n = r >> 2, kt = r & 1, ntl = (r >> 1) & 1;
;             tconv_tile(tile, P.in[mat ? 12 : 10] + ((size_t)l * 8 + n) * 128 * 128, 128, kt * 64, ntl * 64, 0, (bf16_t*)(ws + WS_WAT) + ((size_t)mat * 8 + n) * 128 * 128, 128); }
.Ltc1_d14:
	v_mov_b32_e32 v42, 0
	v_mov_b32_e32 v43, 0
	v_mov_b32_e32 v44, 0
	v_mov_b32_e32 v45, 0
	v_mov_b32_e32 v46, 0
	v_mov_b32_e32 v47, 0
	v_mov_b32_e32 v48, 0
	v_mov_b32_e32 v49, 0
	v_mul_u32_u24_e32 v26, s28, v20
	v_add_lshl_u32 v26, v26, v21, 2
	s_lshl_b32 s0, s28, 7
	v_add_u32_e32 v27, s0, v26
	v_cmp_gt_i32_e32 vcc, s29, v21
	s_and_saveexec_b64 s[0:1], vcc
	global_load_dwordx4 v[42:45], v26, s[26:27]
	global_load_dwordx4 v[46:49], v27, s[26:27]
	s_mov_b64 exec, s[0:1]
	s_add_u32 s24, s24, s34
	s_min_u32 s0, s24, 14015
	s_mov_b32 s21, s0
	s_mov_b32 s0, s21
	s_cmpk_lt_u32 s0, 9600
	s_cbranch_scc0 .Ltc1_c28
	s_and_b32 s1, s0, 31
	s_lshl_b32 s1, s1, 6
	s_lshr_b32 s21, s0, 5
	s_lshl_b32 s21, s21, 6
	s_movk_i32 s29, 64
	s_cmpk_lt_u32 s21, 7680
	s_cbranch_scc1 .Ltc1_n30
	s_cmpk_lt_u32 s21, 18944
	s_cbranch_scc0 .Ltc1_t29
	s_add_u32 s21, s21, 48
	s_branch .Ltc1_n30

; __device__ __forceinline__ void tconv_tile(LAS float* tile, const float* src, int ld, int k0, int n0, int mode, bf16_t* dst, int K) {
;     ...
;     for (int it = 0; it < 2; ++it) { const int idx = tid + it * 512, kk = idx >> 4, n4 = (idx & 15) * 4, nn = n0 + n4; int oc = nn; bool valid = true;
;         if (mode == 1) { if (nn < 7680) oc = nn; else if (nn < 18944) oc = nn + 48; else if (nn < INW) oc = 7680 + (nn - 18944); else valid = false; }
;         f32x4 v = (f32x4){0.f, 0.f, 0.f, 0.f}; if (valid) v = *(const f32x4*)(src + (size_t)(k0 + kk) * ld + oc);
; __device__ __forceinline__ void prologue(LAS unsigned char* lds, const Ctx& P, int l) {
;     ...
;     for (int t = blockIdx.x; t < T_ALL; t += G) {
;         int q = t;
;         if (q < T_IN) { const int kt = q & 31, ntl = q >> 5; tconv_tile(tile, P.in[3] + (size_t)l * DM * INW, INW, kt * 64, ntl * 64, 1, (bf16_t*)(ws + WS_WIN), DM); continue; }
;         q -= T_IN;
;         if (q < T_BR) { const int br = q >> 9, r = q & 511, kt = r & 15, ntl = r >> 4;
;             tconv_tile(tile, P.in[23] + ((size_t)l * 4 + br) * DBR * DM, DM, kt * 64, ntl * 64, 0, (bf16_t*)(ws + WS_WBR) + (size_t)br * DM * DBR, DBR); continue; }
;         q -= T_BR;
;         if (q < T_OUT) { const int kt = q & 31, ntl = q >> 5; tconv_tile(tile, P.in[24] + (size_t)l * DM * DM, DM, kt * 64, ntl * 64, 0, (bf16_t*)(ws + WS_WOUT), DM); continue; }
;         q -= T_OUT;
;         if (q < T_MEM) { const int kt = q & 31, ntl = q >> 5; tconv_tile(tile, P.in[22] + (size_t)l * DM * DM, DM, kt * 64, ntl * 64, 0, (bf16_t*)(ws + WS_WMEM), DM); continue; }
;         q -= T_MEM;
;         if (q < T_W1) { const int kv = q >> 7, r = q & 127, kt = r & 31, ntl = r >> 5;
;             tconv_tile(tile, P.in[17 + kv] + (size_t)l * 2048 * 256, 256, kt * 64, ntl * 64, 0, (bf16_t*)(ws + WS_W1T) + (size_t)kv * 256 * 2048, 2048); continue; }
;         q -= T_W1;
;         { const int mat = q >> 5, r = q & 31, n = r >> 2, kt = r & 1, ntl = (r >> 1) & 1;
;             tconv_tile(tile, P.in[mat ? 12 : 10] + ((size_t)l * 8 + n) * 128 * 128, 128, kt * 64, ntl * 64, 0, (bf16_t*)(ws + WS_WAT) + ((size_t)mat * 8 + n) * 128 * 128, 128); }
.Ltc1_d27:
	v_mov_b32_e32 v50, 0
	v_mov_b32_e32 v51, 0
	v_mov_b32_e32 v52, 0
	v_mov_b32_e32 v53, 0
	v_mov_b32_e32 v54, 0
	v_mov_b32_e32 v55, 0
	v_mov_b32_e32 v56, 0
	v_mov_b32_e32 v57, 0
	v_mul_u32_u24_e32 v26, s28, v20
	v_add_lshl_u32 v26, v26, v21, 2
	s_lshl_b32 s0, s28, 7
	v_add_u32_e32 v27, s0, v26
	v_cmp_gt_i32_e32 vcc, s29, v21
	s_and_saveexec_b64 s[0:1], vcc
	global_load_dwordx4 v[50:53], v26, s[26:27]
	global_load_dwordx4 v[54:57], v27, s[26:27]
	s_mov_b64 exec, s[0:1]
	s_add_u32 s24, s24, s34
	s_min_u32 s0, s24, 14015
	s_mov_b32 s21, s0
	s_mov_b32 s0, s21
	s_cmpk_lt_u32 s0, 9600
	s_cbranch_scc0 .Ltc1_c41
	s_and_b32 s1, s0, 31
	s_lshl_b32 s1, s1, 6
	s_lshr_b32 s21, s0, 5
	s_lshl_b32 s21, s21, 6
	s_movk_i32 s29, 64
	s_cmpk_lt_u32 s21, 7680
	s_cbranch_scc1 .Ltc1_n43
	s_cmpk_lt_u32 s21, 18944
	s_cbranch_scc0 .Ltc1_t42
	s_add_u32 s21, s21, 48
	s_branch .Ltc1_n43

; __device__ __forceinline__ unsigned cvt_pk_bf16(float lo, float hi) { unsigned r; asm("v_cvt_pk_bf16_f32 %0, %1, %2" : "=v"(r) : "v"(lo), "v"(hi)); return r; }
; __device__ __forceinline__ void tconv_tile(LAS float* tile, const float* src, int ld, int k0, int n0, int mode, bf16_t* dst, int K) {
;     ...
;     for (int it = 0; it < 2; ++it) { const int idx = tid + it * 512, kk = idx >> 4, n4 = (idx & 15) * 4, nn = n0 + n4; int oc = nn; bool valid = true;
;         if (mode == 1) { if (nn < 7680) oc = nn; else if (nn < 18944) oc = nn + 48; else if (nn < INW) oc = 7680 + (nn - 18944); else valid = false; }
;         f32x4 v = (f32x4){0.f, 0.f, 0.f, 0.f}; if (valid) v = *(const f32x4*)(src + (size_t)(k0 + kk) * ld + oc);
;         tile[kk * 65 + n4 + 0] = v[0]; tile[kk * 65 + n4 + 1] = v[1]; tile[kk * 65 + n4 + 2] = v[2]; tile[kk * 65 + n4 + 3] = v[3]; }
;     __syncthreads();
;     { const int n = tid >> 3, k8 = (tid & 7) * 8; float v[8];
; #pragma unroll
;         for (int e = 0; e < 8; ++e) v[e] = tile[(k8 + e) * 65 + n];
;         u32x4 w; w.x = cvt_pk_bf16(v[0], v[1]); w.y = cvt_pk_bf16(v[2], v[3]); w.z = cvt_pk_bf16(v[4], v[5]); w.w = cvt_pk_bf16(v[6], v[7]);
;         *(u32x4*)(dst + (size_t)(n0 + n) * K + k0 + k8) = w; }
;     __syncthreads();
; __device__ __forceinline__ void prologue(LAS unsigned char* lds, const Ctx& P, int l) {
;     ...
;     for (int t = blockIdx.x; t < T_ALL; t += G) {
;         int q = t;
;         if (q < T_IN) { const int kt = q & 31, ntl = q >> 5; tconv_tile(tile, P.in[3] + (size_t)l * DM * INW, INW, kt * 64, ntl * 64, 1, (bf16_t*)(ws + WS_WIN), DM); continue; }
;         q -= T_IN;
;         if (q < T_BR) { const int br = q >> 9, r = q & 511, kt = r & 15, ntl = r >> 4;
;             tconv_tile(tile, P.in[23] + ((size_t)l * 4 + br) * DBR * DM, DM, kt * 64, ntl * 64, 0, (bf16_t*)(ws + WS_WBR) + (size_t)br * DM * DBR, DBR); continue; }
;         q -= T_BR;
;         if (q < T_OUT) { const int kt = q & 31, ntl = q >> 5; tconv_tile(tile, P.in[24] + (size_t)l * DM * DM, DM, kt * 64, ntl * 64, 0, (bf16_t*)(ws + WS_WOUT), DM); continue; }
;         q -= T_OUT;
;         if (q < T_MEM) { const int kt = q & 31, ntl = q >> 5; tconv_tile(tile, P.in[22] + (size_t)l * DM * DM, DM, kt * 64, ntl * 64, 0, (bf16_t*)(ws + WS_WMEM), DM); continue; }
;         q -= T_MEM;
;         if (q < T_W1) { const int kv = q >> 7, r = q & 127, kt = r & 31, ntl = r >> 5;
.Ltc1_d40:
	v_mov_b32_e32 v58, 0
	v_mov_b32_e32 v59, 0
	v_mov_b32_e32 v60, 0
	v_mov_b32_e32 v61, 0
	v_mov_b32_e32 v62, 0
	v_mov_b32_e32 v63, 0
	v_mov_b32_e32 v64, 0
	v_mov_b32_e32 v65, 0
	v_mul_u32_u24_e32 v26, s28, v20
	v_add_lshl_u32 v26, v26, v21, 2
	s_lshl_b32 s0, s28, 7
	v_add_u32_e32 v27, s0, v26
	v_cmp_gt_i32_e32 vcc, s29, v21
	s_and_saveexec_b64 s[0:1], vcc
	global_load_dwordx4 v[58:61], v26, s[26:27]
	global_load_dwordx4 v[62:65], v27, s[26:27]
	s_mov_b64 exec, s[0:1]
	s_add_u32 s24, s24, s34
	s_cmpk_ge_u32 s25, 14016
	s_cbranch_scc1 .Ltc1_exit
	s_waitcnt vmcnt(6)
	v_add_u32_e32 v28, 0, v22
	ds_write2_b32 v28, v34, v35 offset1:1
	ds_write2_b32 v28, v36, v37 offset0:2 offset1:3
	v_add_u32_e32 v28, 0x2080, v28
	ds_write2_b32 v28, v38, v39 offset1:1
	ds_write2_b32 v28, v40, v41 offset0:2 offset1:3
	s_mov_b32 s21, s25
	s_mov_b32 s0, s21
	s_cmpk_lt_u32 s0, 9600
	s_cbranch_scc0 .Ltc1_c54
	s_and_b32 s1, s0, 31
	s_lshl_b32 s1, s1, 6
	s_lshr_b32 s21, s0, 5
	s_lshl_b32 s21, s21, 17
	s_add_u32 s1, s1, s21
	s_lshl_b32 s1, s1, 1
	s_add_u32 s1, s1, 0x4001000
	s_add_u32 s30, s68, s1
	s_addc_u32 s31, s69, 0
	s_movk_i32 s20, 0x800
	s_branch .Ltc1_d53
.Ltc1_c54:
	s_sub_u32 s0, s0, 9600
	s_cmpk_lt_u32 s0, 2048
	s_cbranch_scc0 .Ltc1_c55
	s_and_b32 s1, s0, 15
	s_lshl_b32 s1, s1, 6
	s_bfe_u32 s21, s0, 0x50004
	s_lshl_b32 s21, s21, 16
	s_add_u32 s1, s1, s21
	s_lshl_b32 s1, s1, 1
	s_lshr_b32 s21, s0, 9
	s_lshl_b32 s21, s21, 22
	s_add_u32 s1, s1, s21
	s_add_u32 s1, s1, 0x8b01000
	s_add_u32 s30, s68, s1
	s_addc_u32 s31, s69, 0
	s_movk_i32 s20, 0x400
	s_branch .Ltc1_d53
.Ltc1_c55:
	s_sub_u32 s0, s0, 2048
	s_cmpk_lt_u32 s0, 1024
	s_cbranch_scc0 .Ltc1_c56
	s_and_b32 s1, s0, 31
	s_lshl_b32 s1, s1, 6
	s_lshr_b32 s21, s0, 5
	s_lshl_b32 s21, s21, 17
	s_add_u32 s1, s1, s21
	s_lshl_b32 s1, s1, 1
	s_add_u32 s1, s1, 0x9b01000
	s_add_u32 s30, s68, s1
	s_addc_u32 s31, s69, 0
	s_movk_i32 s20, 0x800
	s_branch .Ltc1_d53
.Ltc1_c56:
	s_sub_u32 s0, s0, 1024
	s_cmpk_lt_u32 s0, 1024
	s_cbranch_scc0 .Ltc1_c57
	s_and_b32 s1, s0, 31
	s_lshl_b32 s1, s1, 6
	s_lshr_b32 s21, s0, 5
	s_lshl_b32 s21, s21, 17
	s_add_u32 s1, s1, s21
	s_lshl_b32 s1, s1, 1
	s_add_u32 s1, s1, 0xa301000
	s_add_u32 s30, s68, s1
	s_addc_u32 s31, s69, 0
	s_movk_i32 s20, 0x800
	s_branch .Ltc1_d53
.Ltc1_c57:
	s_sub_u32 s0, s0, 1024
	s_cmpk_lt_u32 s0, 256
	s_cbranch_scc0 .Ltc1_c58
	s_and_b32 s1, s0, 31
	s_lshl_b32 s1, s1, 6
	s_bfe_u32 s21, s0, 0x20005
	s_lshl_b32 s21, s21, 17
	s_add_u32 s1, s1, s21
	s_lshl_b32 s1, s1, 1
	s_lshr_b32 s21, s0, 7
	s_lshl_b32 s21, s21, 20
	s_add_u32 s1, s1, s21
	s_add_u32 s1, s1, 0xaf01000
	s_add_u32 s30, s68, s1
	s_addc_u32 s31, s69, 0
	s_movk_i32 s20, 0x800
	s_branch .Ltc1_d53
.Ltc1_c58:
	s_sub_u32 s0, s0, 256
	s_and_b32 s1, s0, 1
	s_lshl_b32 s1, s1, 6
	s_bfe_u32 s21, s0, 0x10001
	s_lshl_b32 s21, s21, 13
	s_add_u32 s1, s1, s21
	s_lshl_b32 s1, s1, 1
	s_lshr_b32 s21, s0, 2
	s_lshl_b32 s21, s21, 15
	s_add_u32 s1, s1, s21
	s_add_u32 s1, s1, 0xb101000
	s_add_u32 s30, s68, s1
	s_addc_u32 s31, s69, 0
	s_movk_i32 s20, 0x80
.Ltc1_d53:
	v_mul_u32_u24_e32 v29, s20, v24
	v_add_lshl_u32 v29, v29, v25, 1
	s_waitcnt lgkmcnt(0)
	s_barrier
	v_add_u32_e32 v28, 0, v23
	ds_read2_b32 v[2:3], v28 offset1:65
	ds_read2_b32 v[4:5], v28 offset0:130 offset1:195
	v_add_u32_e32 v28, 0x400, v28
	ds_read2_b32 v[6:7], v28 offset0:4 offset1:69
	ds_read2_b32 v[10:11], v28 offset0:134 offset1:199
	s_waitcnt lgkmcnt(3)
	v_cvt_pk_bf16_f32 v2, v2, v3
	s_waitcnt lgkmcnt(2)
	v_cvt_pk_bf16_f32 v3, v4, v5
	s_waitcnt lgkmcnt(1)
	v_cvt_pk_bf16_f32 v4, v6, v7
	s_waitcnt lgkmcnt(0)
	v_cvt_pk_bf16_f32 v5, v10, v11
	global_store_dwordx4 v29, v[2:5], s[30:31]
	s_add_u32 s25, s25, s34
	s_min_u32 s0, s24, 14015
	s_mov_b32 s21, s0
	s_mov_b32 s0, s21
	s_cmpk_lt_u32 s0, 9600
	s_cbranch_scc0 .Ltc1_c61
	s_and_b32 s1, s0, 31
	s_lshl_b32 s1, s1, 6
	s_lshr_b32 s21, s0, 5
	s_lshl_b32 s21, s21, 6
	s_movk_i32 s29, 64
	s_cmpk_lt_u32 s21, 7680
	s_cbranch_scc1 .Ltc1_n63
	s_cmpk_lt_u32 s21, 18944
	s_cbranch_scc0 .Ltc1_t62
	s_add_u32 s21, s21, 48
	s_branch .Ltc1_n63

; __device__ __forceinline__ unsigned cvt_pk_bf16(float lo, float hi) { unsigned r; asm("v_cvt_pk_bf16_f32 %0, %1, %2" : "=v"(r) : "v"(lo), "v"(hi)); return r; }
; __device__ __forceinline__ void tconv_tile(LAS float* tile, const float* src, int ld, int k0, int n0, int mode, bf16_t* dst, int K) {
;     ...
;     for (int it = 0; it < 2; ++it) { const int idx = tid + it * 512, kk = idx >> 4, n4 = (idx & 15) * 4, nn = n0 + n4; int oc = nn; bool valid = true;
;         if (mode == 1) { if (nn < 7680) oc = nn; else if (nn < 18944) oc = nn + 48; else if (nn < INW) oc = 7680 + (nn - 18944); else valid = false; }
;         f32x4 v = (f32x4){0.f, 0.f, 0.f, 0.f}; if (valid) v = *(const f32x4*)(src + (size_t)(k0 + kk) * ld + oc);
;         tile[kk * 65 + n4 + 0] = v[0]; tile[kk * 65 + n4 + 1] = v[1]; tile[kk * 65 + n4 + 2] = v[2]; tile[kk * 65 + n4 + 3] = v[3]; }
;     __syncthreads();
;     { const int n = tid >> 3, k8 = (tid & 7) * 8; float v[8];
; #pragma unroll
;         for (int e = 0; e < 8; ++e) v[e] = tile[(k8 + e) * 65 + n];
;         u32x4 w; w.x = cvt_pk_bf16(v[0], v[1]); w.y = cvt_pk_bf16(v[2], v[3]); w.z = cvt_pk_bf16(v[4], v[5]); w.w = cvt_pk_bf16(v[6], v[7]);
;         *(u32x4*)(dst + (size_t)(n0 + n) * K + k0 + k8) = w; }
; __device__ __forceinline__ void prologue(LAS unsigned char* lds, const Ctx& P, int l) {
;     ...
;     for (int t = blockIdx.x; t < T_ALL; t += G) {
;         int q = t;
;         if (q < T_IN) { const int kt = q & 31, ntl = q >> 5; tconv_tile(tile, P.in[3] + (size_t)l * DM * INW, INW, kt * 64, ntl * 64, 1, (bf16_t*)(ws + WS_WIN), DM); continue; }
;         q -= T_IN;
;         if (q < T_BR) { const int br = q >> 9, r = q & 511, kt = r & 15, ntl = r >> 4;
;             tconv_tile(tile, P.in[23] + ((size_t)l * 4 + br) * DBR * DM, DM, kt * 64, ntl * 64, 0, (bf16_t*)(ws + WS_WBR) + (size_t)br * DM * DBR, DBR); continue; }
;         q -= T_BR;
;         if (q < T_OUT) { const int kt = q & 31, ntl = q >> 5; tconv_tile(tile, P.in[24] + (size_t)l * DM * DM, DM, kt * 64, ntl * 64, 0, (bf16_t*)(ws + WS_WOUT), DM); continue; }
.Ltc1_d60:
	v_mov_b32_e32 v34, 0
	v_mov_b32_e32 v35, 0
	v_mov_b32_e32 v36, 0
	v_mov_b32_e32 v37, 0
	v_mov_b32_e32 v38, 0
	v_mov_b32_e32 v39, 0
	v_mov_b32_e32 v40, 0
	v_mov_b32_e32 v41, 0
	v_mul_u32_u24_e32 v26, s28, v20
	v_add_lshl_u32 v26, v26, v21, 2
	s_lshl_b32 s0, s28, 7
	v_add_u32_e32 v27, s0, v26
	v_cmp_gt_i32_e32 vcc, s29, v21
	s_and_saveexec_b64 s[0:1], vcc
	global_load_dwordx4 v[34:37], v26, s[26:27]
	global_load_dwordx4 v[38:41], v27, s[26:27]
	s_mov_b64 exec, s[0:1]
	s_add_u32 s24, s24, s34
	s_cmpk_ge_u32 s25, 14016
	s_cbranch_scc1 .Ltc1_exit
	s_waitcnt vmcnt(7)
	v_add_u32_e32 v28, 16896, v22
	ds_write2_b32 v28, v42, v43 offset1:1
	ds_write2_b32 v28, v44, v45 offset0:2 offset1:3
	v_add_u32_e32 v28, 0x2080, v28
	ds_write2_b32 v28, v46, v47 offset1:1
	ds_write2_b32 v28, v48, v49 offset0:2 offset1:3
	s_mov_b32 s21, s25
	s_mov_b32 s0, s21
	s_cmpk_lt_u32 s0, 9600
	s_cbranch_scc0 .Ltc1_c74
	s_and_b32 s1, s0, 31
	s_lshl_b32 s1, s1, 6
	s_lshr_b32 s21, s0, 5
	s_lshl_b32 s21, s21, 17
	s_add_u32 s1, s1, s21
	s_lshl_b32 s1, s1, 1
	s_add_u32 s1, s1, 0x4001000
	s_add_u32 s30, s68, s1
	s_addc_u32 s31, s69, 0
	s_movk_i32 s20, 0x800
	s_branch .Ltc1_d73

; __device__ __forceinline__ unsigned cvt_pk_bf16(float lo, float hi) { unsigned r; asm("v_cvt_pk_bf16_f32 %0, %1, %2" : "=v"(r) : "v"(lo), "v"(hi)); return r; }
; __device__ __forceinline__ void tconv_tile(LAS float* tile, const float* src, int ld, int k0, int n0, int mode, bf16_t* dst, int K) {
;     ...
;     { const int n = tid >> 3, k8 = (tid & 7) * 8; float v[8];
; #pragma unroll
;         for (int e = 0; e < 8; ++e) v[e] = tile[(k8 + e) * 65 + n];
;         u32x4 w; w.x = cvt_pk_bf16(v[0], v[1]); w.y = cvt_pk_bf16(v[2], v[3]); w.z = cvt_pk_bf16(v[4], v[5]); w.w = cvt_pk_bf16(v[6], v[7]);
;         *(u32x4*)(dst + (size_t)(n0 + n) * K + k0 + k8) = w; }
; __device__ __forceinline__ void prologue(LAS unsigned char* lds, const Ctx& P, int l) {
;     ...
;     for (int t = blockIdx.x; t < T_ALL; t += G) {
;         int q = t;
;         if (q < T_IN) { const int kt = q & 31, ntl = q >> 5; tconv_tile(tile, P.in[3] + (size_t)l * DM * INW, INW, kt * 64, ntl * 64, 1, (bf16_t*)(ws + WS_WIN), DM); continue; }
;         q -= T_IN;
;         if (q < T_BR) { const int br = q >> 9, r = q & 511, kt = r & 15, ntl = r >> 4;
;             tconv_tile(tile, P.in[23] + ((size_t)l * 4 + br) * DBR * DM, DM, kt * 64, ntl * 64, 0, (bf16_t*)(ws + WS_WBR) + (size_t)br * DM * DBR, DBR); continue; }
;         q -= T_BR;
;         if (q < T_OUT) { const int kt = q & 31, ntl = q >> 5; tconv_tile(tile, P.in[24] + (size_t)l * DM * DM, DM, kt * 64, ntl * 64, 0, (bf16_t*)(ws + WS_WOUT), DM); continue; }
.Ltc1_d73:
	v_mul_u32_u24_e32 v29, s20, v24
	v_add_lshl_u32 v29, v29, v25, 1
	s_waitcnt lgkmcnt(0)
	s_barrier
	v_add_u32_e32 v28, 16896, v23
	ds_read2_b32 v[2:3], v28 offset1:65
	ds_read2_b32 v[4:5], v28 offset0:130 offset1:195
	v_add_u32_e32 v28, 0x400, v28
	ds_read2_b32 v[6:7], v28 offset0:4 offset1:69
	ds_read2_b32 v[10:11], v28 offset0:134 offset1:199
	s_waitcnt lgkmcnt(3)
	v_cvt_pk_bf16_f32 v2, v2, v3
	s_waitcnt lgkmcnt(2)
	v_cvt_pk_bf16_f32 v3, v4, v5
	s_waitcnt lgkmcnt(1)
	v_cvt_pk_bf16_f32 v4, v6, v7
	s_waitcnt lgkmcnt(0)
	v_cvt_pk_bf16_f32 v5, v10, v11
	global_store_dwordx4 v29, v[2:5], s[30:31]
	s_add_u32 s25, s25, s34
	s_min_u32 s0, s24, 14015
	s_mov_b32 s21, s0
	s_mov_b32 s0, s21
	s_cmpk_lt_u32 s0, 9600
	s_cbranch_scc0 .Ltc1_c81
	s_and_b32 s1, s0, 31
	s_lshl_b32 s1, s1, 6
	s_lshr_b32 s21, s0, 5
	s_lshl_b32 s21, s21, 6
	s_movk_i32 s29, 64
	s_cmpk_lt_u32 s21, 7680
	s_cbranch_scc1 .Ltc1_n83
	s_cmpk_lt_u32 s21, 18944
	s_cbranch_scc0 .Ltc1_t82
	s_add_u32 s21, s21, 48
	s_branch .Ltc1_n83

; __device__ __forceinline__ unsigned cvt_pk_bf16(float lo, float hi) { unsigned r; asm("v_cvt_pk_bf16_f32 %0, %1, %2" : "=v"(r) : "v"(lo), "v"(hi)); return r; }
; __device__ __forceinline__ void tconv_tile(LAS float* tile, const float* src, int ld, int k0, int n0, int mode, bf16_t* dst, int K) {
;     ...
;     for (int it = 0; it < 2; ++it) { const int idx = tid + it * 512, kk = idx >> 4, n4 = (idx & 15) * 4, nn = n0 + n4; int oc = nn; bool valid = true;
;         if (mode == 1) { if (nn < 7680) oc = nn; else if (nn < 18944) oc = nn + 48; else if (nn < INW) oc = 7680 + (nn - 18944); else valid = false; }
;         f32x4 v = (f32x4){0.f, 0.f, 0.f, 0.f}; if (valid) v = *(const f32x4*)(src + (size_t)(k0 + kk) * ld + oc);
;         tile[kk * 65 + n4 + 0] = v[0]; tile[kk * 65 + n4 + 1] = v[1]; tile[kk * 65 + n4 + 2] = v[2]; tile[kk * 65 + n4 + 3] = v[3]; }
;     __syncthreads();
;     { const int n = tid >> 3, k8 = (tid & 7) * 8; float v[8];
; #pragma unroll
;         for (int e = 0; e < 8; ++e) v[e] = tile[(k8 + e) * 65 + n];
;         u32x4 w; w.x = cvt_pk_bf16(v[0], v[1]); w.y = cvt_pk_bf16(v[2], v[3]); w.z = cvt_pk_bf16(v[4], v[5]); w.w = cvt_pk_bf16(v[6], v[7]);
;         *(u32x4*)(dst + (size_t)(n0 + n) * K + k0 + k8) = w; }
; __device__ __forceinline__ void prologue(LAS unsigned char* lds, const Ctx& P, int l) {
;     ...
;     for (int t = blockIdx.x; t < T_ALL; t += G) {
;         int q = t;
;         if (q < T_IN) { const int kt = q & 31, ntl = q >> 5; tconv_tile(tile, P.in[3] + (size_t)l * DM * INW, INW, kt * 64, ntl * 64, 1, (bf16_t*)(ws + WS_WIN), DM); continue; }
;         q -= T_IN;
;         if (q < T_BR) { const int br = q >> 9, r = q & 511, kt = r & 15, ntl = r >> 4;
;             tconv_tile(tile, P.in[23] + ((size_t)l * 4 + br) * DBR * DM, DM, kt * 64, ntl * 64, 0, (bf16_t*)(ws + WS_WBR) + (size_t)br * DM * DBR, DBR); continue; }
;         q -= T_BR;
;         if (q < T_OUT) { const int kt = q & 31, ntl = q >> 5; tconv_tile(tile, P.in[24] + (size_t)l * DM * DM, DM, kt * 64, ntl * 64, 0, (bf16_t*)(ws + WS_WOUT), DM); continue; }
.Ltc1_d80:
	v_mov_b32_e32 v42, 0
	v_mov_b32_e32 v43, 0
	v_mov_b32_e32 v44, 0
	v_mov_b32_e32 v45, 0
	v_mov_b32_e32 v46, 0
	v_mov_b32_e32 v47, 0
	v_mov_b32_e32 v48, 0
	v_mov_b32_e32 v49, 0
	v_mul_u32_u24_e32 v26, s28, v20
	v_add_lshl_u32 v26, v26, v21, 2
	s_lshl_b32 s0, s28, 7
	v_add_u32_e32 v27, s0, v26
	v_cmp_gt_i32_e32 vcc, s29, v21
	s_and_saveexec_b64 s[0:1], vcc
	global_load_dwordx4 v[42:45], v26, s[26:27]
	global_load_dwordx4 v[46:49], v27, s[26:27]
	s_mov_b64 exec, s[0:1]
	s_add_u32 s24, s24, s34
	s_cmpk_ge_u32 s25, 14016
	s_cbranch_scc1 .Ltc1_exit
	s_waitcnt vmcnt(8)
	v_add_u32_e32 v28, 0, v22
	ds_write2_b32 v28, v50, v51 offset1:1
	ds_write2_b32 v28, v52, v53 offset0:2 offset1:3
	v_add_u32_e32 v28, 0x2080, v28
	ds_write2_b32 v28, v54, v55 offset1:1
	ds_write2_b32 v28, v56, v57 offset0:2 offset1:3
	s_mov_b32 s21, s25
	s_mov_b32 s0, s21
	s_cmpk_lt_u32 s0, 9600
	s_cbranch_scc0 .Ltc1_c94
	s_and_b32 s1, s0, 31
	s_lshl_b32 s1, s1, 6
	s_lshr_b32 s21, s0, 5
	s_lshl_b32 s21, s21, 17
	s_add_u32 s1, s1, s21
	s_lshl_b32 s1, s1, 1
	s_add_u32 s1, s1, 0x4001000
	s_add_u32 s30, s68, s1
	s_addc_u32 s31, s69, 0
	s_movk_i32 s20, 0x800
	s_branch .Ltc1_d93

; __device__ __forceinline__ unsigned cvt_pk_bf16(float lo, float hi) { unsigned r; asm("v_cvt_pk_bf16_f32 %0, %1, %2" : "=v"(r) : "v"(lo), "v"(hi)); return r; }
; __device__ __forceinline__ void tconv_tile(LAS float* tile, const float* src, int ld, int k0, int n0, int mode, bf16_t* dst, int K) {
;     ...
;     for (int it = 0; it < 2; ++it) { const int idx = tid + it * 512, kk = idx >> 4, n4 = (idx & 15) * 4, nn = n0 + n4; int oc = nn; bool valid = true;
;         if (mode == 1) { if (nn < 7680) oc = nn; else if (nn < 18944) oc = nn + 48; else if (nn < INW) oc = 7680 + (nn - 18944); else valid = false; }
;         f32x4 v = (f32x4){0.f, 0.f, 0.f, 0.f}; if (valid) v = *(const f32x4*)(src + (size_t)(k0 + kk) * ld + oc);
;         tile[kk * 65 + n4 + 0] = v[0]; tile[kk * 65 + n4 + 1] = v[1]; tile[kk * 65 + n4 + 2] = v[2]; tile[kk * 65 + n4 + 3] = v[3]; }
;     __syncthreads();
;     { const int n = tid >> 3, k8 = (tid & 7) * 8; float v[8];
; #pragma unroll
;         for (int e = 0; e < 8; ++e) v[e] = tile[(k8 + e) * 65 + n];
;         u32x4 w; w.x = cvt_pk_bf16(v[0], v[1]); w.y = cvt_pk_bf16(v[2], v[3]); w.z = cvt_pk_bf16(v[4], v[5]); w.w = cvt_pk_bf16(v[6], v[7]);
;         *(u32x4*)(dst + (size_t)(n0 + n) * K + k0 + k8) = w; }
; __device__ __forceinline__ void prologue(LAS unsigned char* lds, const Ctx& P, int l) {
;     ...
;     for (int t = blockIdx.x; t < T_ALL; t += G) {
;         int q = t;
;         if (q < T_IN) { const int kt = q & 31, ntl = q >> 5; tconv_tile(tile, P.in[3] + (size_t)l * DM * INW, INW, kt * 64, ntl * 64, 1, (bf16_t*)(ws + WS_WIN), DM); continue; }
;         q -= T_IN;
;         if (q < T_BR) { const int br = q >> 9, r = q & 511, kt = r & 15, ntl = r >> 4;
;             tconv_tile(tile, P.in[23] + ((size_t)l * 4 + br) * DBR * DM, DM, kt * 64, ntl * 64, 0, (bf16_t*)(ws + WS_WBR) + (size_t)br * DM * DBR, DBR); continue; }
;         q -= T_BR;
;         if (q < T_OUT) { const int kt = q & 31, ntl = q >> 5; tconv_tile(tile, P.in[24] + (size_t)l * DM * DM, DM, kt * 64, ntl * 64, 0, (bf16_t*)(ws + WS_WOUT), DM); continue; }
.Ltc1_d100:
	v_mov_b32_e32 v50, 0
	v_mov_b32_e32 v51, 0
	v_mov_b32_e32 v52, 0
	v_mov_b32_e32 v53, 0
	v_mov_b32_e32 v54, 0
	v_mov_b32_e32 v55, 0
	v_mov_b32_e32 v56, 0
	v_mov_b32_e32 v57, 0
	v_mul_u32_u24_e32 v26, s28, v20
	v_add_lshl_u32 v26, v26, v21, 2
	s_lshl_b32 s0, s28, 7
	v_add_u32_e32 v27, s0, v26
	v_cmp_gt_i32_e32 vcc, s29, v21
	s_and_saveexec_b64 s[0:1], vcc
	global_load_dwordx4 v[50:53], v26, s[26:27]
	global_load_dwordx4 v[54:57], v27, s[26:27]
	s_mov_b64 exec, s[0:1]
	s_add_u32 s24, s24, s34
	s_cmpk_ge_u32 s25, 14016
	s_cbranch_scc1 .Ltc1_exit
	s_waitcnt vmcnt(9)
	v_add_u32_e32 v28, 16896, v22
	ds_write2_b32 v28, v58, v59 offset1:1
	ds_write2_b32 v28, v60, v61 offset0:2 offset1:3
	v_add_u32_e32 v28, 0x2080, v28
	ds_write2_b32 v28, v62, v63 offset1:1
	ds_write2_b32 v28, v64, v65 offset0:2 offset1:3
	s_mov_b32 s21, s25
	s_mov_b32 s0, s21
	s_cmpk_lt_u32 s0, 9600
	s_cbranch_scc0 .Ltc1_c114
	s_and_b32 s1, s0, 31
	s_lshl_b32 s1, s1, 6
	s_lshr_b32 s21, s0, 5
	s_lshl_b32 s21, s21, 17
	s_add_u32 s1, s1, s21
	s_lshl_b32 s1, s1, 1
	s_add_u32 s1, s1, 0x4001000
	s_add_u32 s30, s68, s1
	s_addc_u32 s31, s69, 0
	s_movk_i32 s20, 0x800
	s_branch .Ltc1_d113

; __device__ __forceinline__ unsigned cvt_pk_bf16(float lo, float hi) { unsigned r; asm("v_cvt_pk_bf16_f32 %0, %1, %2" : "=v"(r) : "v"(lo), "v"(hi)); return r; }
; __device__ __forceinline__ void tconv_tile(LAS float* tile, const float* src, int ld, int k0, int n0, int mode, bf16_t* dst, int K) {
;     ...
;     for (int it = 0; it < 2; ++it) { const int idx = tid + it * 512, kk = idx >> 4, n4 = (idx & 15) * 4, nn = n0 + n4; int oc = nn; bool valid = true;
;         if (mode == 1) { if (nn < 7680) oc = nn; else if (nn < 18944) oc = nn + 48; else if (nn < INW) oc = 7680 + (nn - 18944); else valid = false; }
;         f32x4 v = (f32x4){0.f, 0.f, 0.f, 0.f}; if (valid) v = *(const f32x4*)(src + (size_t)(k0 + kk) * ld + oc);
;         tile[kk * 65 + n4 + 0] = v[0]; tile[kk * 65 + n4 + 1] = v[1]; tile[kk * 65 + n4 + 2] = v[2]; tile[kk * 65 + n4 + 3] = v[3]; }
;     __syncthreads();
;     { const int n = tid >> 3, k8 = (tid & 7) * 8; float v[8];
; #pragma unroll
;         for (int e = 0; e < 8; ++e) v[e] = tile[(k8 + e) * 65 + n];
;         u32x4 w; w.x = cvt_pk_bf16(v[0], v[1]); w.y = cvt_pk_bf16(v[2], v[3]); w.z = cvt_pk_bf16(v[4], v[5]); w.w = cvt_pk_bf16(v[6], v[7]);
;         *(u32x4*)(dst + (size_t)(n0 + n) * K + k0 + k8) = w; }
; __device__ __forceinline__ void prologue(LAS unsigned char* lds, const Ctx& P, int l) {
;     ...
;     for (int t = blockIdx.x; t < T_ALL; t += G) {
;         int q = t;
;         if (q < T_IN) { const int kt = q & 31, ntl = q >> 5; tconv_tile(tile, P.in[3] + (size_t)l * DM * INW, INW, kt * 64, ntl * 64, 1, (bf16_t*)(ws + WS_WIN), DM); continue; }
;         q -= T_IN;
;         if (q < T_BR) { const int br = q >> 9, r = q & 511, kt = r & 15, ntl = r >> 4;
;             tconv_tile(tile, P.in[23] + ((size_t)l * 4 + br) * DBR * DM, DM, kt * 64, ntl * 64, 0, (bf16_t*)(ws + WS_WBR) + (size_t)br * DM * DBR, DBR); continue; }
;         q -= T_BR;
;         if (q < T_OUT) { const int kt = q & 31, ntl = q >> 5; tconv_tile(tile, P.in[24] + (size_t)l * DM * DM, DM, kt * 64, ntl * 64, 0, (bf16_t*)(ws + WS_WOUT), DM); continue; }
.Ltc1_d120:
	v_mov_b32_e32 v58, 0
	v_mov_b32_e32 v59, 0
	v_mov_b32_e32 v60, 0
	v_mov_b32_e32 v61, 0
	v_mov_b32_e32 v62, 0
	v_mov_b32_e32 v63, 0
	v_mov_b32_e32 v64, 0
	v_mov_b32_e32 v65, 0
	v_mul_u32_u24_e32 v26, s28, v20
	v_add_lshl_u32 v26, v26, v21, 2
	s_lshl_b32 s0, s28, 7
	v_add_u32_e32 v27, s0, v26
	v_cmp_gt_i32_e32 vcc, s29, v21
	s_and_saveexec_b64 s[0:1], vcc
	global_load_dwordx4 v[58:61], v26, s[26:27]
	global_load_dwordx4 v[62:65], v27, s[26:27]
	s_mov_b64 exec, s[0:1]
	s_add_u32 s24, s24, s34
.Ltc1_loop:
	s_cmpk_ge_u32 s25, 14016
	s_cbranch_scc1 .Ltc1_exit
	s_waitcnt vmcnt(9)
	v_add_u32_e32 v28, 0, v22
	ds_write2_b32 v28, v34, v35 offset1:1
	ds_write2_b32 v28, v36, v37 offset0:2 offset1:3
	v_add_u32_e32 v28, 0x2080, v28
	ds_write2_b32 v28, v38, v39 offset1:1
	ds_write2_b32 v28, v40, v41 offset0:2 offset1:3
	s_mov_b32 s21, s25
	s_mov_b32 s0, s21
	s_cmpk_lt_u32 s0, 9600
	s_cbranch_scc0 .Ltc1_c134
	s_and_b32 s1, s0, 31
	s_lshl_b32 s1, s1, 6
	s_lshr_b32 s21, s0, 5
	s_lshl_b32 s21, s21, 17
	s_add_u32 s1, s1, s21
	s_lshl_b32 s1, s1, 1
	s_add_u32 s1, s1, 0x4001000
	s_add_u32 s30, s68, s1
	s_addc_u32 s31, s69, 0
	s_movk_i32 s20, 0x800
	s_branch .Ltc1_d133

; __device__ __forceinline__ unsigned cvt_pk_bf16(float lo, float hi) { unsigned r; asm("v_cvt_pk_bf16_f32 %0, %1, %2" : "=v"(r) : "v"(lo), "v"(hi)); return r; }
; __device__ __forceinline__ void tconv_tile(LAS float* tile, const float* src, int ld, int k0, int n0, int mode, bf16_t* dst, int K) {
;     ...
;     for (int it = 0; it < 2; ++it) { const int idx = tid + it * 512, kk = idx >> 4, n4 = (idx & 15) * 4, nn = n0 + n4; int oc = nn; bool valid = true;
;         if (mode == 1) { if (nn < 7680) oc = nn; else if (nn < 18944) oc = nn + 48; else if (nn < INW) oc = 7680 + (nn - 18944); else valid = false; }
;         f32x4 v = (f32x4){0.f, 0.f, 0.f, 0.f}; if (valid) v = *(const f32x4*)(src + (size_t)(k0 + kk) * ld + oc);
;         tile[kk * 65 + n4 + 0] = v[0]; tile[kk * 65 + n4 + 1] = v[1]; tile[kk * 65 + n4 + 2] = v[2]; tile[kk * 65 + n4 + 3] = v[3]; }
;     __syncthreads();
;     { const int n = tid >> 3, k8 = (tid & 7) * 8; float v[8];
; #pragma unroll
;         for (int e = 0; e < 8; ++e) v[e] = tile[(k8 + e) * 65 + n];
;         u32x4 w; w.x = cvt_pk_bf16(v[0], v[1]); w.y = cvt_pk_bf16(v[2], v[3]); w.z = cvt_pk_bf16(v[4], v[5]); w.w = cvt_pk_bf16(v[6], v[7]);
;         *(u32x4*)(dst + (size_t)(n0 + n) * K + k0 + k8) = w; }
; __device__ __forceinline__ void prologue(LAS unsigned char* lds, const Ctx& P, int l) {
;     ...
;     for (int t = blockIdx.x; t < T_ALL; t += G) {
;         int q = t;
;         if (q < T_IN) { const int kt = q & 31, ntl = q >> 5; tconv_tile(tile, P.in[3] + (size_t)l * DM * INW, INW, kt * 64, ntl * 64, 1, (bf16_t*)(ws + WS_WIN), DM); continue; }
;         q -= T_IN;
;         if (q < T_BR) { const int br = q >> 9, r = q & 511, kt = r & 15, ntl = r >> 4;
;             tconv_tile(tile, P.in[23] + ((size_t)l * 4 + br) * DBR * DM, DM, kt * 64, ntl * 64, 0, (bf16_t*)(ws + WS_WBR) + (size_t)br * DM * DBR, DBR); continue; }
;         q -= T_BR;
;         if (q < T_OUT) { const int kt = q & 31, ntl = q >> 5; tconv_tile(tile, P.in[24] + (size_t)l * DM * DM, DM, kt * 64, ntl * 64, 0, (bf16_t*)(ws + WS_WOUT), DM); continue; }
.Ltc1_d140:
	v_mov_b32_e32 v34, 0
	v_mov_b32_e32 v35, 0
	v_mov_b32_e32 v36, 0
	v_mov_b32_e32 v37, 0
	v_mov_b32_e32 v38, 0
	v_mov_b32_e32 v39, 0
	v_mov_b32_e32 v40, 0
	v_mov_b32_e32 v41, 0
	v_mul_u32_u24_e32 v26, s28, v20
	v_add_lshl_u32 v26, v26, v21, 2
	s_lshl_b32 s0, s28, 7
	v_add_u32_e32 v27, s0, v26
	v_cmp_gt_i32_e32 vcc, s29, v21
	s_and_saveexec_b64 s[0:1], vcc
	global_load_dwordx4 v[34:37], v26, s[26:27]
	global_load_dwordx4 v[38:41], v27, s[26:27]
	s_mov_b64 exec, s[0:1]
	s_add_u32 s24, s24, s34
	s_cmpk_ge_u32 s25, 14016
	s_cbranch_scc1 .Ltc1_exit
	s_waitcnt vmcnt(9)
	v_add_u32_e32 v28, 16896, v22
	ds_write2_b32 v28, v42, v43 offset1:1
	ds_write2_b32 v28, v44, v45 offset0:2 offset1:3
	v_add_u32_e32 v28, 0x2080, v28
	ds_write2_b32 v28, v46, v47 offset1:1
	ds_write2_b32 v28, v48, v49 offset0:2 offset1:3
	s_mov_b32 s21, s25
	s_mov_b32 s0, s21
	s_cmpk_lt_u32 s0, 9600
	s_cbranch_scc0 .Ltc1_c154
	s_and_b32 s1, s0, 31
	s_lshl_b32 s1, s1, 6
	s_lshr_b32 s21, s0, 5
	s_lshl_b32 s21, s21, 17
	s_add_u32 s1, s1, s21
	s_lshl_b32 s1, s1, 1
	s_add_u32 s1, s1, 0x4001000
	s_add_u32 s30, s68, s1
	s_addc_u32 s31, s69, 0
	s_movk_i32 s20, 0x800
	s_branch .Ltc1_d153

; __device__ __forceinline__ unsigned cvt_pk_bf16(float lo, float hi) { unsigned r; asm("v_cvt_pk_bf16_f32 %0, %1, %2" : "=v"(r) : "v"(lo), "v"(hi)); return r; }
; __device__ __forceinline__ void tconv_tile(LAS float* tile, const float* src, int ld, int k0, int n0, int mode, bf16_t* dst, int K) {
;     ...
;     for (int it = 0; it < 2; ++it) { const int idx = tid + it * 512, kk = idx >> 4, n4 = (idx & 15) * 4, nn = n0 + n4; int oc = nn; bool valid = true;
;         if (mode == 1) { if (nn < 7680) oc = nn; else if (nn < 18944) oc = nn + 48; else if (nn < INW) oc = 7680 + (nn - 18944); else valid = false; }
;         f32x4 v = (f32x4){0.f, 0.f, 0.f, 0.f}; if (valid) v = *(const f32x4*)(src + (size_t)(k0 + kk) * ld + oc);
;         tile[kk * 65 + n4 + 0] = v[0]; tile[kk * 65 + n4 + 1] = v[1]; tile[kk * 65 + n4 + 2] = v[2]; tile[kk * 65 + n4 + 3] = v[3]; }
;     __syncthreads();
;     { const int n = tid >> 3, k8 = (tid & 7) * 8; float v[8];
; #pragma unroll
;         for (int e = 0; e < 8; ++e) v[e] = tile[(k8 + e) * 65 + n];
;         u32x4 w; w.x = cvt_pk_bf16(v[0], v[1]); w.y = cvt_pk_bf16(v[2], v[3]); w.z = cvt_pk_bf16(v[4], v[5]); w.w = cvt_pk_bf16(v[6], v[7]);
;         *(u32x4*)(dst + (size_t)(n0 + n) * K + k0 + k8) = w; }
; __device__ __forceinline__ void prologue(LAS unsigned char* lds, const Ctx& P, int l) {
;     ...
;     for (int t = blockIdx.x; t < T_ALL; t += G) {
;         int q = t;
;         if (q < T_IN) { const int kt = q & 31, ntl = q >> 5; tconv_tile(tile, P.in[3] + (size_t)l * DM * INW, INW, kt * 64, ntl * 64, 1, (bf16_t*)(ws + WS_WIN), DM); continue; }
;         q -= T_IN;
;         if (q < T_BR) { const int br = q >> 9, r = q & 511, kt = r & 15, ntl = r >> 4;
;             tconv_tile(tile, P.in[23] + ((size_t)l * 4 + br) * DBR * DM, DM, kt * 64, ntl * 64, 0, (bf16_t*)(ws + WS_WBR) + (size_t)br * DM * DBR, DBR); continue; }
;         q -= T_BR;
;         if (q < T_OUT) { const int kt = q & 31, ntl = q >> 5; tconv_tile(tile, P.in[24] + (size_t)l * DM * DM, DM, kt * 64, ntl * 64, 0, (bf16_t*)(ws + WS_WOUT), DM); continue; }
.Ltc1_d160:
	v_mov_b32_e32 v42, 0
	v_mov_b32_e32 v43, 0
	v_mov_b32_e32 v44, 0
	v_mov_b32_e32 v45, 0
	v_mov_b32_e32 v46, 0
	v_mov_b32_e32 v47, 0
	v_mov_b32_e32 v48, 0
	v_mov_b32_e32 v49, 0
	v_mul_u32_u24_e32 v26, s28, v20
	v_add_lshl_u32 v26, v26, v21, 2
	s_lshl_b32 s0, s28, 7
	v_add_u32_e32 v27, s0, v26
	v_cmp_gt_i32_e32 vcc, s29, v21
	s_and_saveexec_b64 s[0:1], vcc
	global_load_dwordx4 v[42:45], v26, s[26:27]
	global_load_dwordx4 v[46:49], v27, s[26:27]
	s_mov_b64 exec, s[0:1]
	s_add_u32 s24, s24, s34
	s_cmpk_ge_u32 s25, 14016
	s_cbranch_scc1 .Ltc1_exit
	s_waitcnt vmcnt(9)
	v_add_u32_e32 v28, 0, v22
	ds_write2_b32 v28, v50, v51 offset1:1
	ds_write2_b32 v28, v52, v53 offset0:2 offset1:3
	v_add_u32_e32 v28, 0x2080, v28
	ds_write2_b32 v28, v54, v55 offset1:1
	ds_write2_b32 v28, v56, v57 offset0:2 offset1:3
	s_mov_b32 s21, s25
	s_mov_b32 s0, s21
	s_cmpk_lt_u32 s0, 9600
	s_cbranch_scc0 .Ltc1_c174
	s_and_b32 s1, s0, 31
	s_lshl_b32 s1, s1, 6
	s_lshr_b32 s21, s0, 5
	s_lshl_b32 s21, s21, 17
	s_add_u32 s1, s1, s21
	s_lshl_b32 s1, s1, 1
	s_add_u32 s1, s1, 0x4001000
	s_add_u32 s30, s68, s1
	s_addc_u32 s31, s69, 0
	s_movk_i32 s20, 0x800
	s_branch .Ltc1_d173

; #define LAS __attribute__((address_space(3)))
; __device__ __forceinline__ void tconv_tile(LAS float* tile, const float* src, int ld, int k0, int n0, int mode, bf16_t* dst, int K) {
;     const int tid = opaque_tid();
; #pragma unroll
;     for (int it = 0; it < 2; ++it) { const int idx = tid + it * 512, kk = idx >> 4, n4 = (idx & 15) * 4, nn = n0 + n4; int oc = nn; bool valid = true;
;         if (mode == 1) { if (nn < 7680) oc = nn; else if (nn < 18944) oc = nn + 48; else if (nn < INW) oc = 7680 + (nn - 18944); else valid = false; }
;         f32x4 v = (f32x4){0.f, 0.f, 0.f, 0.f}; if (valid) v = *(const f32x4*)(src + (size_t)(k0 + kk) * ld + oc);
;         tile[kk * 65 + n4 + 0] = v[0]; tile[kk * 65 + n4 + 1] = v[1]; tile[kk * 65 + n4 + 2] = v[2]; tile[kk * 65 + n4 + 3] = v[3]; }
;     __syncthreads();
;     { const int n = tid >> 3, k8 = (tid & 7) * 8; float v[8];
; #pragma unroll
;         for (int e = 0; e < 8; ++e) v[e] = tile[(k8 + e) * 65 + n];
;         u32x4 w; w.x = cvt_pk_bf16(v[0], v[1]); w.y = cvt_pk_bf16(v[2], v[3]); w.z = cvt_pk_bf16(v[4], v[5]); w.w = cvt_pk_bf16(v[6], v[7]);
;         *(u32x4*)(dst + (size_t)(n0 + n) * K + k0 + k8) = w; }
;     __syncthreads();
; __device__ __forceinline__ void prologue(LAS unsigned char* lds, const Ctx& P, int l) {
;     ...
;     for (int t = blockIdx.x; t < T_ALL; t += G) {
;         int q = t;
;         if (q < T_IN) { const int kt = q & 31, ntl = q >> 5; tconv_tile(tile, P.in[3] + (size_t)l * DM * INW, INW, kt * 64, ntl * 64, 1, (bf16_t*)(ws + WS_WIN), DM); continue; }
;         q -= T_IN;
;         if (q < T_BR) { const int br = q >> 9, r = q & 511, kt = r & 15, ntl = r >> 4;
;             tconv_tile(tile, P.in[23] + ((size_t)l * 4 + br) * DBR * DM, DM, kt * 64, ntl * 64, 0, (bf16_t*)(ws + WS_WBR) + (size_t)br * DM * DBR, DBR); continue; }
;         q -= T_BR;
;         if (q < T_OUT) { const int kt = q & 31, ntl = q >> 5; tconv_tile(tile, P.in[24] + (size_t)l * DM * DM, DM, kt * 64, ntl * 64, 0, (bf16_t*)(ws + WS_WOUT), DM); continue; }
;         q -= T_OUT;
;         if (q < T_MEM) { const int kt = q & 31, ntl = q >> 5; tconv_tile(tile, P.in[22] + (size_t)l * DM * DM, DM, kt * 64, ntl * 64, 0, (bf16_t*)(ws + WS_WMEM), DM); continue; }
;         q -= T_MEM;
;         if (q < T_W1) { const int kv = q >> 7, r = q & 127, kt = r & 31, ntl = r >> 5;
.Ltc1_d200:
	v_mov_b32_e32 v58, 0
	v_mov_b32_e32 v59, 0
	v_mov_b32_e32 v60, 0
	v_mov_b32_e32 v61, 0
	v_mov_b32_e32 v62, 0
	v_mov_b32_e32 v63, 0
	v_mov_b32_e32 v64, 0
	v_mov_b32_e32 v65, 0
	v_mul_u32_u24_e32 v26, s28, v20
	v_add_lshl_u32 v26, v26, v21, 2
	s_lshl_b32 s0, s28, 7
	v_add_u32_e32 v27, s0, v26
	v_cmp_gt_i32_e32 vcc, s29, v21
	s_and_saveexec_b64 s[0:1], vcc
	global_load_dwordx4 v[58:61], v26, s[26:27]
	global_load_dwordx4 v[62:65], v27, s[26:27]
	s_mov_b64 exec, s[0:1]
	s_add_u32 s24, s24, s34
	s_branch .Ltc1_loop
.Ltc1_exit:
	s_waitcnt vmcnt(0)
	s_barrier
	s_branch .LBB0_891

; __device__ __forceinline__ void prologue(LAS unsigned char* lds, const Ctx& P, int l) {
;     ...
;     for (int u = blockIdx.x; u < 8; u += G) { const int kv = u >> 2, cb = u & 3, col = cb * 64 + (tid & 63), ks = tid >> 6;
;         const float* pe = P.in[15 + kv] + (size_t)l * 2048; const float* w1 = P.in[17 + kv] + (size_t)l * 2048 * 256; float s = 0.f;
;         for (int k = ks * 256; k < ks * 256 + 256; ++k) s += pe[k] * w1[(size_t)k * 256 + col];
;         tile[tid] = s; __syncthreads();
;         if (tid < 64) { float a = 0.f;
; #pragma unroll
;             for (int j = 0; j < 8; ++j) a += tile[j * 64 + tid];
;             ((float*)(ws + WS_PEW1))[kv * 256 + col] = a; }
;         __syncthreads(); }
.LBB0_902:
	global_load_dword v34, v[12:13], off
	global_load_dword v50, v[10:11], off
	v_lshl_add_u64 v[10:11], v[10:11], 0, s[96:97]
	global_load_dword v35, v[12:13], off offset:4
	global_load_dword v51, v[10:11], off
	v_lshl_add_u64 v[10:11], v[10:11], 0, s[96:97]
	global_load_dword v36, v[12:13], off offset:8
	global_load_dword v52, v[10:11], off
	v_lshl_add_u64 v[10:11], v[10:11], 0, s[96:97]
	global_load_dword v37, v[12:13], off offset:12
	global_load_dword v53, v[10:11], off
	v_lshl_add_u64 v[10:11], v[10:11], 0, s[96:97]
	global_load_dword v38, v[12:13], off offset:16
	global_load_dword v54, v[10:11], off
	v_lshl_add_u64 v[10:11], v[10:11], 0, s[96:97]
	global_load_dword v39, v[12:13], off offset:20
	global_load_dword v55, v[10:11], off
	v_lshl_add_u64 v[10:11], v[10:11], 0, s[96:97]
	global_load_dword v40, v[12:13], off offset:24
	global_load_dword v56, v[10:11], off
	v_lshl_add_u64 v[10:11], v[10:11], 0, s[96:97]
	global_load_dword v41, v[12:13], off offset:28
	global_load_dword v57, v[10:11], off
	v_lshl_add_u64 v[10:11], v[10:11], 0, s[96:97]
	global_load_dword v42, v[12:13], off offset:32
	global_load_dword v58, v[10:11], off
	v_lshl_add_u64 v[10:11], v[10:11], 0, s[96:97]
	global_load_dword v43, v[12:13], off offset:36
	global_load_dword v59, v[10:11], off
	v_lshl_add_u64 v[10:11], v[10:11], 0, s[96:97]
	global_load_dword v44, v[12:13], off offset:40
	global_load_dword v60, v[10:11], off
	v_lshl_add_u64 v[10:11], v[10:11], 0, s[96:97]
	global_load_dword v45, v[12:13], off offset:44
	global_load_dword v61, v[10:11], off
	v_lshl_add_u64 v[10:11], v[10:11], 0, s[96:97]
	global_load_dword v46, v[12:13], off offset:48
	global_load_dword v62, v[10:11], off
	v_lshl_add_u64 v[10:11], v[10:11], 0, s[96:97]
	global_load_dword v47, v[12:13], off offset:52
	global_load_dword v63, v[10:11], off
	v_lshl_add_u64 v[10:11], v[10:11], 0, s[96:97]
	global_load_dword v48, v[12:13], off offset:56
	global_load_dword v64, v[10:11], off
	v_lshl_add_u64 v[10:11], v[10:11], 0, s[96:97]
	global_load_dword v49, v[12:13], off offset:60
	global_load_dword v65, v[10:11], off
	v_lshl_add_u64 v[10:11], v[10:11], 0, s[96:97]
	v_lshl_add_u64 v[12:13], v[12:13], 0, 64
	v_add_u32_e32 v18, 16, v18
	v_cmp_ge_i32_e64 s[0:1], v18, v16
	s_or_b64 s[6:7], s[0:1], s[6:7]
	s_waitcnt vmcnt(30)
	v_fmac_f32_e32 v0, v34, v50
	s_waitcnt vmcnt(28)
	v_fmac_f32_e32 v0, v35, v51
	s_waitcnt vmcnt(26)
	v_fmac_f32_e32 v0, v36, v52
	s_waitcnt vmcnt(24)
	v_fmac_f32_e32 v0, v37, v53
	s_waitcnt vmcnt(22)
	v_fmac_f32_e32 v0, v38, v54
	s_waitcnt vmcnt(20)
	v_fmac_f32_e32 v0, v39, v55
	s_waitcnt vmcnt(18)
	v_fmac_f32_e32 v0, v40, v56
	s_waitcnt vmcnt(16)
	v_fmac_f32_e32 v0, v41, v57
	s_waitcnt vmcnt(14)
	v_fmac_f32_e32 v0, v42, v58
	s_waitcnt vmcnt(12)
	v_fmac_f32_e32 v0, v43, v59
	s_waitcnt vmcnt(10)
	v_fmac_f32_e32 v0, v44, v60
	s_waitcnt vmcnt(8)
	v_fmac_f32_e32 v0, v45, v61
	s_waitcnt vmcnt(6)
	v_fmac_f32_e32 v0, v46, v62
	s_waitcnt vmcnt(4)
	v_fmac_f32_e32 v0, v47, v63
	s_waitcnt vmcnt(2)
	v_fmac_f32_e32 v0, v48, v64
	s_waitcnt vmcnt(0)
	v_fmac_f32_e32 v0, v49, v65
	s_andn2_b64 exec, exec, s[6:7]
	s_cbranch_execnz .LBB0_902
	s_or_b64 exec, exec, s[6:7]
	ds_write_b32 v15, v0
	s_waitcnt lgkmcnt(0)
	s_barrier
	s_and_saveexec_b64 s[0:1], vcc
	s_cbranch_execz .LBB0_900
	ds_read2st64_b32 v[10:11], v15 offset1:1
	s_lshl_b32 s6, s9, 6
	s_and_b32 s6, s6, 0xc0
	v_or_b32_e32 v0, s6, v14
	s_waitcnt lgkmcnt(0)
	v_add_f32_e32 v10, 0, v10
	v_add_f32_e32 v12, v10, v11
	ds_read2st64_b32 v[10:11], v15 offset0:2 offset1:3
	s_waitcnt lgkmcnt(0)
	v_add_f32_e32 v10, v12, v10
	v_add_f32_e32 v12, v10, v11
	ds_read2st64_b32 v[10:11], v15 offset0:4 offset1:5
	s_waitcnt lgkmcnt(0)
	v_add_f32_e32 v10, v12, v10
	v_add_f32_e32 v12, v10, v11
	ds_read2st64_b32 v[10:11], v15 offset0:6 offset1:7
	s_waitcnt lgkmcnt(0)
	v_add_f32_e32 v10, v12, v10
	v_add_f32_e32 v12, v10, v11
	v_lshl_or_b32 v10, s12, 8, v0
	v_ashrrev_i32_e32 v11, 31, v10
	v_lshl_add_u64 v[10:11], v[10:11], 2, s[4:5]
	global_store_dword v[10:11], v12, off
	s_branch .LBB0_900

; #define LAS __attribute__((address_space(3)))
; __device__ __forceinline__ int opaque_tid() { int t = threadIdx.x; asm volatile("" : "+v"(t)); return t; }
; __device__ __forceinline__ void tconv_tile(LAS float* tile, const float* src, int ld, int k0, int n0, int mode, bf16_t* dst, int K) {
;     const int tid = opaque_tid();
; #pragma unroll
;     for (int it = 0; it < 2; ++it) { const int idx = tid + it * 512, kk = idx >> 4, n4 = (idx & 15) * 4, nn = n0 + n4; int oc = nn; bool valid = true;
;         if (mode == 1) { if (nn < 7680) oc = nn; else if (nn < 18944) oc = nn + 48; else if (nn < INW) oc = 7680 + (nn - 18944); else valid = false; }
;         f32x4 v = (f32x4){0.f, 0.f, 0.f, 0.f}; if (valid) v = *(const f32x4*)(src + (size_t)(k0 + kk) * ld + oc);
; __device__ __forceinline__ void prologue(LAS unsigned char* lds, const Ctx& P, int l) {
;     unsigned char* ws = P.ws; LAS float* tile = (LAS float*)lds;
;     const int tid = opaque_tid(), G = gridDim.x;
;     const int T_IN = 32 * 300, T_BR = 4 * 512, T_OUT = 1024, T_MEM = 1024, T_W1 = 256, T_WA = 64;
;     const int T_ALL = T_IN + T_BR + T_OUT + T_MEM + T_W1 + T_WA;
;     for (int t = blockIdx.x; t < T_ALL; t += G) {
;         int q = t;
;         if (q < T_IN) { const int kt = q & 31, ntl = q >> 5; tconv_tile(tile, P.in[3] + (size_t)l * DM * INW, INW, kt * 64, ntl * 64, 1, (bf16_t*)(ws + WS_WIN), DM); continue; }
.LBB0_1011:
	v_mov_b32_e32 v26, 0x23f00
	ds_read_b64 v[34:35], v26 offset:24
	ds_read_b64 v[36:37], v26 offset:184
	ds_read_b64 v[38:39], v26 offset:192
	ds_read_b64 v[40:41], v26 offset:176
	ds_read_b64 v[42:43], v26 offset:136
	ds_read_b64 v[44:45], v26 offset:144
	ds_read_b64 v[46:47], v26 offset:80
	ds_read_b64 v[48:49], v26 offset:96
	s_waitcnt lgkmcnt(0)
	v_readfirstlane_b32 s4, v34
	v_readfirstlane_b32 s5, v35
	v_readfirstlane_b32 s6, v36
	v_readfirstlane_b32 s7, v37
	v_readfirstlane_b32 s8, v38
	v_readfirstlane_b32 s9, v39
	v_readfirstlane_b32 s10, v40
	v_readfirstlane_b32 s11, v41
	v_readfirstlane_b32 s12, v42
	v_readfirstlane_b32 s13, v43
	v_readfirstlane_b32 s14, v44
	v_readfirstlane_b32 s15, v45
	v_readfirstlane_b32 s16, v46
	v_readfirstlane_b32 s17, v47
	v_readfirstlane_b32 s18, v48
	v_readfirstlane_b32 s19, v49
	v_lshrrev_b32_e32 v20, 4, v234
	v_and_b32_e32 v21, 15, v234
	v_lshlrev_b32_e32 v21, 2, v21
	v_mul_u32_u24_e32 v22, 0x104, v20
	v_lshl_add_u32 v22, v21, 2, v22
	v_lshrrev_b32_e32 v24, 3, v234
	v_and_b32_e32 v25, 7, v234
	v_lshlrev_b32_e32 v25, 3, v25
	v_mul_u32_u24_e32 v23, 0x104, v25
	v_lshl_add_u32 v23, v24, 2, v23
	s_mov_b32 s24, s2
	s_mov_b32 s25, s2
	s_min_u32 s0, s24, 14015
	s_mov_b32 s21, s0
	s_mov_b32 s0, s21
	s_cmpk_lt_u32 s0, 9600
	s_cbranch_scc0 .Ltc0_c2
	s_and_b32 s1, s0, 31
	s_lshl_b32 s1, s1, 6
	s_lshr_b32 s21, s0, 5
	s_lshl_b32 s21, s21, 6
	s_movk_i32 s29, 64
	s_cmpk_lt_u32 s21, 7680
	s_cbranch_scc1 .Ltc0_n4
	s_cmpk_lt_u32 s21, 18944
	s_cbranch_scc0 .Ltc0_t3
	s_add_u32 s21, s21, 48
	s_branch .Ltc0_n4

; __device__ __forceinline__ void prologue(LAS unsigned char* lds, const Ctx& P, int l) {
;     ...
;     for (int u = blockIdx.x; u < 8; u += G) { const int kv = u >> 2, cb = u & 3, col = cb * 64 + (tid & 63), ks = tid >> 6;
;         const float* pe = P.in[15 + kv] + (size_t)l * 2048; const float* w1 = P.in[17 + kv] + (size_t)l * 2048 * 256; float s = 0.f;
;         for (int k = ks * 256; k < ks * 256 + 256; ++k) s += pe[k] * w1[(size_t)k * 256 + col];
;         tile[tid] = s; __syncthreads();
;         if (tid < 64) { float a = 0.f;
; #pragma unroll
;             for (int j = 0; j < 8; ++j) a += tile[j * 64 + tid];
;             ((float*)(ws + WS_PEW1))[kv * 256 + col] = a; }
;         __syncthreads(); }
.LBB0_1045:
	global_load_dword v34, v[8:9], off
	global_load_dword v50, v[6:7], off
	v_lshl_add_u64 v[6:7], v[6:7], 0, s[96:97]
	global_load_dword v35, v[8:9], off offset:4
	global_load_dword v51, v[6:7], off
	v_lshl_add_u64 v[6:7], v[6:7], 0, s[96:97]
	global_load_dword v36, v[8:9], off offset:8
	global_load_dword v52, v[6:7], off
	v_lshl_add_u64 v[6:7], v[6:7], 0, s[96:97]
	global_load_dword v37, v[8:9], off offset:12
	global_load_dword v53, v[6:7], off
	v_lshl_add_u64 v[6:7], v[6:7], 0, s[96:97]
	global_load_dword v38, v[8:9], off offset:16
	global_load_dword v54, v[6:7], off
	v_lshl_add_u64 v[6:7], v[6:7], 0, s[96:97]
	global_load_dword v39, v[8:9], off offset:20
	global_load_dword v55, v[6:7], off
	v_lshl_add_u64 v[6:7], v[6:7], 0, s[96:97]
	global_load_dword v40, v[8:9], off offset:24
	global_load_dword v56, v[6:7], off
	v_lshl_add_u64 v[6:7], v[6:7], 0, s[96:97]
	global_load_dword v41, v[8:9], off offset:28
	global_load_dword v57, v[6:7], off
	v_lshl_add_u64 v[6:7], v[6:7], 0, s[96:97]
	global_load_dword v42, v[8:9], off offset:32
	global_load_dword v58, v[6:7], off
	v_lshl_add_u64 v[6:7], v[6:7], 0, s[96:97]
	global_load_dword v43, v[8:9], off offset:36
	global_load_dword v59, v[6:7], off
	v_lshl_add_u64 v[6:7], v[6:7], 0, s[96:97]
	global_load_dword v44, v[8:9], off offset:40
	global_load_dword v60, v[6:7], off
	v_lshl_add_u64 v[6:7], v[6:7], 0, s[96:97]
	global_load_dword v45, v[8:9], off offset:44
	global_load_dword v61, v[6:7], off
	v_lshl_add_u64 v[6:7], v[6:7], 0, s[96:97]
	global_load_dword v46, v[8:9], off offset:48
	global_load_dword v62, v[6:7], off
	v_lshl_add_u64 v[6:7], v[6:7], 0, s[96:97]
	global_load_dword v47, v[8:9], off offset:52
	global_load_dword v63, v[6:7], off
	v_lshl_add_u64 v[6:7], v[6:7], 0, s[96:97]
	global_load_dword v48, v[8:9], off offset:56
	global_load_dword v64, v[6:7], off
	v_lshl_add_u64 v[6:7], v[6:7], 0, s[96:97]
	global_load_dword v49, v[8:9], off offset:60
	global_load_dword v65, v[6:7], off
	v_lshl_add_u64 v[6:7], v[6:7], 0, s[96:97]
	v_lshl_add_u64 v[8:9], v[8:9], 0, 64
	v_add_u32_e32 v14, 16, v14
	v_cmp_ge_i32_e64 s[0:1], v14, v12
	s_or_b64 s[8:9], s[0:1], s[8:9]
	s_waitcnt vmcnt(30)
	v_fmac_f32_e32 v0, v34, v50
	s_waitcnt vmcnt(28)
	v_fmac_f32_e32 v0, v35, v51
	s_waitcnt vmcnt(26)
	v_fmac_f32_e32 v0, v36, v52
	s_waitcnt vmcnt(24)
	v_fmac_f32_e32 v0, v37, v53
	s_waitcnt vmcnt(22)
	v_fmac_f32_e32 v0, v38, v54
	s_waitcnt vmcnt(20)
	v_fmac_f32_e32 v0, v39, v55
	s_waitcnt vmcnt(18)
	v_fmac_f32_e32 v0, v40, v56
	s_waitcnt vmcnt(16)
	v_fmac_f32_e32 v0, v41, v57
	s_waitcnt vmcnt(14)
	v_fmac_f32_e32 v0, v42, v58
	s_waitcnt vmcnt(12)
	v_fmac_f32_e32 v0, v43, v59
	s_waitcnt vmcnt(10)
	v_fmac_f32_e32 v0, v44, v60
	s_waitcnt vmcnt(8)
	v_fmac_f32_e32 v0, v45, v61
	s_waitcnt vmcnt(6)
	v_fmac_f32_e32 v0, v46, v62
	s_waitcnt vmcnt(4)
	v_fmac_f32_e32 v0, v47, v63
	s_waitcnt vmcnt(2)
	v_fmac_f32_e32 v0, v48, v64
	s_waitcnt vmcnt(0)
	v_fmac_f32_e32 v0, v49, v65
	s_andn2_b64 exec, exec, s[8:9]
	s_cbranch_execnz .LBB0_1045
	s_or_b64 exec, exec, s[8:9]
	ds_write_b32 v11, v0
	s_waitcnt lgkmcnt(0)
	s_barrier
	s_and_saveexec_b64 s[0:1], vcc
	s_cbranch_execz .LBB0_1043
	ds_read2st64_b32 v[6:7], v11 offset1:1
	ds_read2st64_b32 v[8:9], v11 offset0:2 offset1:3
	ds_read2st64_b32 v[14:15], v11 offset0:4 offset1:5
	ds_read2st64_b32 v[16:17], v11 offset0:6 offset1:7
	s_lshl_b32 s8, s11, 6
	s_and_b32 s8, s8, 0xc0
	v_or_b32_e32 v0, s8, v10
	s_waitcnt lgkmcnt(3)
	v_add_f32_e32 v6, 0, v6
	v_add_f32_e32 v6, v6, v7
	s_waitcnt lgkmcnt(2)
	v_add_f32_e32 v6, v6, v8
	v_add_f32_e32 v6, v6, v9
	s_waitcnt lgkmcnt(1)
	v_add_f32_e32 v6, v6, v14
	v_add_f32_e32 v6, v6, v15
	s_waitcnt lgkmcnt(0)
	v_add_f32_e32 v6, v6, v16
	v_add_f32_e32 v8, v6, v17
	v_lshl_or_b32 v6, s12, 8, v0
	v_ashrrev_i32_e32 v7, 31, v6
	v_lshl_add_u64 v[6:7], v[6:7], 2, s[4:5]
	global_store_dword v[6:7], v8, off
	s_branch .LBB0_1043
